# nt cache policy on the proj GEMM (sp0) epilogue stores: streaming r1 output no longer pollutes L2/MALL
# speedup vs baseline: 1.1675x; 1.1675x over previous
; #define PG8_STAGE(bufoff, gbase, voff) do { _Pragma("unroll") for (int _i = 0; _i < 2; ++_i) \
;         __builtin_amdgcn_global_load_lds((const unsigned*)((const char*)(gbase) + (size_t)_i * p64##voff + (v##voff##_)), (LAS unsigned*)(lds + (bufoff) + ldsw + _i * 8192), 16, 0, 0); } while (0)
; #define PG8_LDA(dst, b, h) do { _Pragma("unroll") for (int m = 0; m < 4; ++m) _Pragma("unroll") for (int k = 0; k < 2; ++k) dst[m][k] = *(const LAS bf16x8*)(lds + PG8_SA(b, h) + aoff + m * 2048 + k * 1024); } while (0)
; #define PG8_LDB(dst, b, h) do { _Pragma("unroll") for (int n = 0; n < 2; ++n) _Pragma("unroll") for (int k = 0; k < 2; ++k) dst[n][k] = *(const LAS bf16x8*)(lds + PG8_SB(b, h) + boff + n * 2048 + k * 1024); } while (0)
; #define PG8_MMA(ai, bj, At, Bt) do { __builtin_amdgcn_s_setprio(1); _Pragma("unroll") for (int m = 0; m < 4; ++m) _Pragma("unroll") for (int n = 0; n < 2; ++n) _Pragma("unroll") for (int k = 0; k < 2; ++k) \
;         acc[ai][bj][m][n] = __builtin_amdgcn_mfma_f32_16x16x32_bf16(Bt[n][k], At[m][k], acc[ai][bj][m][n], 0, 0, 0); __builtin_amdgcn_s_setprio(0); } while (0)
; #define PG8_WAIT_L(n) asm volatile("s_waitcnt lgkmcnt(" #n ")" ::: "memory")
; #define PG8_BAR __builtin_amdgcn_s_barrier()
; #define PG8_SCHED __builtin_amdgcn_sched_barrier(0)
; template <class Epi, class Sched>
; DI void gemm_phase(LAS unsigned char* lds, const Gemm g, const Sched& S, const Epi& E, const int tid) {
;     ...
;         for (int t = 0; t < nt; t += 2) {
;             const bool last = (t == nt - 2);
;             const char* a1 = cA + (size_t)(t + 1) * kstep;
;             const char* a2 = last ? nA : cA + (size_t)(t + 2) * kstep; const char* b2 = last ? nB : cB + (size_t)(t + 2) * kstep;
;             const char* a3 = a2 + kstep; const char* b3 = b2 + kstep;
;             PG8_LDB(B0, 0, 0); PG8_SCHED; PG8_LDA(At, 0, 0); PG8_STAGE(PG8_SA(1, 1), a1 + hstepA, offA);
;             PG8_WAIT_L(8); PG8_BAR; PG8_WAIT_L(0); PG8_MMA(0, 0, At, B0); PG8_BAR; PG8_SCHED;
;             PG8_LDB(B1, 0, 1); PG8_STAGE(PG8_SB(0, 0), b2, offB);
;             PG8_BAR; PG8_WAIT_L(0); PG8_MMA(0, 1, At, B1); PG8_BAR;
;             PG8_LDA(At, 0, 1); PG8_STAGE(PG8_SA(0, 0), a2, offA);
;             PG8_BAR; PG8_WAIT_L(0); PG8_MMA(1, 0, At, B0); PG8_BAR; PG8_SCHED;
.LBB0_556:
	s_add_u32 s57, s40, 0xfffc0080
	s_addc_u32 s58, s41, -1
	s_add_i32 s62, 0, 0x10000
	v_add_u32_e32 v146, s62, v143
	ds_read_b128 v[152:155], v146
	ds_read_b128 v[156:159], v146 offset:1024
	ds_read_b128 v[160:163], v146 offset:2048
	ds_read_b128 v[164:167], v146 offset:3072
	s_cmp_eq_u32 s56, 12
	s_cselect_b32 s59, s5, s58
	s_cselect_b32 s58, s54, s57
	s_cselect_b32 s61, s1, s43
	s_cselect_b32 s60, s55, s42
	v_lshl_add_u64 v[146:147], s[40:41], 0, v[132:133]
	s_add_i32 m0, s45, 0xc000
	ds_read_b128 v[168:171], v145
	ds_read_b128 v[172:175], v145 offset:1024
	ds_read_b128 v[176:179], v145 offset:2048
	ds_read_b128 v[180:183], v145 offset:3072
	ds_read_b128 v[184:187], v145 offset:4096
	ds_read_b128 v[188:191], v145 offset:5120
	ds_read_b128 v[212:215], v145 offset:6144
	ds_read_b128 v[216:219], v145 offset:7168
	global_load_lds_dwordx4 v[146:147], off
	v_lshl_add_u64 v[146:147], v[146:147], 0, s[10:11]
	s_add_i32 m0, s45, 0xe000
	s_nop 0
	global_load_lds_dwordx4 v[146:147], off
	s_waitcnt lgkmcnt(8)
	s_barrier
	s_waitcnt lgkmcnt(0)
	s_setprio 1
	s_waitcnt lgkmcnt(0)
	v_mfma_f32_16x16x32_bf16 v[126:129], v[152:155], v[168:171], v[126:129]
	v_mfma_f32_16x16x32_bf16 v[122:125], v[160:163], v[168:171], v[122:125]
	v_mfma_f32_16x16x32_bf16 v[118:121], v[152:155], v[176:179], v[118:121]
	v_mfma_f32_16x16x32_bf16 v[114:117], v[160:163], v[176:179], v[114:117]
	v_mfma_f32_16x16x32_bf16 v[102:105], v[152:155], v[184:187], v[102:105]
	v_mfma_f32_16x16x32_bf16 v[98:101], v[160:163], v[184:187], v[98:101]
	v_mfma_f32_16x16x32_bf16 v[86:89], v[152:155], v[212:215], v[86:89]
	v_mfma_f32_16x16x32_bf16 v[82:85], v[160:163], v[212:215], v[82:85]
	v_mfma_f32_16x16x32_bf16 v[126:129], v[156:159], v[172:175], v[126:129]
	v_mfma_f32_16x16x32_bf16 v[122:125], v[164:167], v[172:175], v[122:125]
	v_mfma_f32_16x16x32_bf16 v[118:121], v[156:159], v[180:183], v[118:121]
	v_mfma_f32_16x16x32_bf16 v[114:117], v[164:167], v[180:183], v[114:117]
	v_mfma_f32_16x16x32_bf16 v[102:105], v[156:159], v[188:191], v[102:105]
	v_mfma_f32_16x16x32_bf16 v[98:101], v[164:167], v[188:191], v[98:101]
	v_mfma_f32_16x16x32_bf16 v[86:89], v[156:159], v[216:219], v[86:89]
	v_mfma_f32_16x16x32_bf16 v[82:85], v[164:167], v[216:219], v[82:85]
	s_setprio 0
	s_barrier
	s_add_i32 s57, 0, 0x14000
	v_add_u32_e32 v146, s57, v143
	ds_read_b128 v[220:223], v146
	ds_read_b128 v[224:227], v146 offset:1024
	ds_read_b128 v[228:231], v146 offset:2048
	ds_read_b128 v[244:247], v146 offset:3072
	v_lshl_add_u64 v[146:147], s[60:61], 0, v[0:1]
	s_add_i32 s60, s62, s44
	s_mov_b32 m0, s60
	v_lshl_add_u64 v[192:193], v[146:147], 0, s[10:11]
	global_load_lds_dwordx4 v[146:147], off
	s_add_i32 m0, s60, 0x2000
	s_nop 0
	global_load_lds_dwordx4 v[192:193], off
	s_barrier
	s_waitcnt lgkmcnt(0)
	s_setprio 1
	s_waitcnt lgkmcnt(0)
	v_mfma_f32_16x16x32_bf16 v[110:113], v[220:223], v[168:171], v[110:113]
	v_mfma_f32_16x16x32_bf16 v[106:109], v[228:231], v[168:171], v[106:109]
	v_mfma_f32_16x16x32_bf16 v[94:97], v[220:223], v[176:179], v[94:97]
	v_mfma_f32_16x16x32_bf16 v[90:93], v[228:231], v[176:179], v[90:93]
	v_mfma_f32_16x16x32_bf16 v[78:81], v[220:223], v[184:187], v[78:81]
	v_mfma_f32_16x16x32_bf16 v[74:77], v[228:231], v[184:187], v[74:77]
	v_mfma_f32_16x16x32_bf16 v[70:73], v[220:223], v[212:215], v[70:73]
	v_mfma_f32_16x16x32_bf16 v[66:69], v[228:231], v[212:215], v[66:69]
	v_mfma_f32_16x16x32_bf16 v[110:113], v[224:227], v[172:175], v[110:113]
	v_mfma_f32_16x16x32_bf16 v[106:109], v[244:247], v[172:175], v[106:109]
	v_mfma_f32_16x16x32_bf16 v[94:97], v[224:227], v[180:183], v[94:97]
	v_mfma_f32_16x16x32_bf16 v[90:93], v[244:247], v[180:183], v[90:93]
	v_mfma_f32_16x16x32_bf16 v[78:81], v[224:227], v[188:191], v[78:81]
	v_mfma_f32_16x16x32_bf16 v[74:77], v[244:247], v[188:191], v[74:77]
	v_mfma_f32_16x16x32_bf16 v[70:73], v[224:227], v[216:219], v[70:73]
	v_mfma_f32_16x16x32_bf16 v[66:69], v[244:247], v[216:219], v[66:69]
	s_setprio 0
	s_mov_b32 m0, s45
	v_lshl_add_u64 v[192:193], s[58:59], 0, v[130:131]
	s_barrier
	ds_read_b128 v[168:171], v145 offset:16384
	ds_read_b128 v[172:175], v145 offset:17408
	ds_read_b128 v[176:179], v145 offset:18432
	ds_read_b128 v[180:183], v145 offset:19456
	ds_read_b128 v[184:187], v145 offset:20480
	ds_read_b128 v[188:191], v145 offset:21504
	ds_read_b128 v[212:215], v145 offset:22528
	ds_read_b128 v[216:219], v145 offset:23552
	global_load_lds_dwordx4 v[192:193], off
	v_lshl_add_u64 v[248:249], v[192:193], 0, s[10:11]
	s_mov_b32 m0, s46
	s_nop 0
	global_load_lds_dwordx4 v[248:249], off
	s_barrier
	s_waitcnt lgkmcnt(0)
	s_setprio 1
	s_waitcnt lgkmcnt(0)
	v_mfma_f32_16x16x32_bf16 v[62:65], v[152:155], v[168:171], v[62:65]
	v_mfma_f32_16x16x32_bf16 v[58:61], v[160:163], v[168:171], v[58:61]
	v_mfma_f32_16x16x32_bf16 v[54:57], v[152:155], v[176:179], v[54:57]
	v_mfma_f32_16x16x32_bf16 v[50:53], v[160:163], v[176:179], v[50:53]
	v_mfma_f32_16x16x32_bf16 v[38:41], v[152:155], v[184:187], v[38:41]
	v_mfma_f32_16x16x32_bf16 v[34:37], v[160:163], v[184:187], v[34:37]
	v_mfma_f32_16x16x32_bf16 v[22:25], v[152:155], v[212:215], v[22:25]
	v_mfma_f32_16x16x32_bf16 v[18:21], v[160:163], v[212:215], v[18:21]
	v_mfma_f32_16x16x32_bf16 v[62:65], v[156:159], v[172:175], v[62:65]
	v_mfma_f32_16x16x32_bf16 v[58:61], v[164:167], v[172:175], v[58:61]
	v_mfma_f32_16x16x32_bf16 v[54:57], v[156:159], v[180:183], v[54:57]
	v_mfma_f32_16x16x32_bf16 v[50:53], v[164:167], v[180:183], v[50:53]
	v_mfma_f32_16x16x32_bf16 v[38:41], v[156:159], v[188:191], v[38:41]
	v_mfma_f32_16x16x32_bf16 v[34:37], v[164:167], v[188:191], v[34:37]
	v_mfma_f32_16x16x32_bf16 v[22:25], v[156:159], v[216:219], v[22:25]
	v_mfma_f32_16x16x32_bf16 v[18:21], v[164:167], v[216:219], v[18:21]
	s_setprio 0
	s_barrier
; #define PG8_STAGE(bufoff, gbase, voff) do { _Pragma("unroll") for (int _i = 0; _i < 2; ++_i) \
;         __builtin_amdgcn_global_load_lds((const unsigned*)((const char*)(gbase) + (size_t)_i * p64##voff + (v##voff##_)), (LAS unsigned*)(lds + (bufoff) + ldsw + _i * 8192), 16, 0, 0); } while (0)
; #define PG8_LDA(dst, b, h) do { _Pragma("unroll") for (int m = 0; m < 4; ++m) _Pragma("unroll") for (int k = 0; k < 2; ++k) dst[m][k] = *(const LAS bf16x8*)(lds + PG8_SA(b, h) + aoff + m * 2048 + k * 1024); } while (0)
; #define PG8_LDB(dst, b, h) do { _Pragma("unroll") for (int n = 0; n < 2; ++n) _Pragma("unroll") for (int k = 0; k < 2; ++k) dst[n][k] = *(const LAS bf16x8*)(lds + PG8_SB(b, h) + boff + n * 2048 + k * 1024); } while (0)
; #define PG8_MMA(ai, bj, At, Bt) do { __builtin_amdgcn_s_setprio(1); _Pragma("unroll") for (int m = 0; m < 4; ++m) _Pragma("unroll") for (int n = 0; n < 2; ++n) _Pragma("unroll") for (int k = 0; k < 2; ++k) \
;         acc[ai][bj][m][n] = __builtin_amdgcn_mfma_f32_16x16x32_bf16(Bt[n][k], At[m][k], acc[ai][bj][m][n], 0, 0, 0); __builtin_amdgcn_s_setprio(0); } while (0)
; #define PG8_WAIT_V(n) asm volatile("s_waitcnt vmcnt(" #n ")" ::: "memory")
; #define PG8_WAIT_L(n) asm volatile("s_waitcnt lgkmcnt(" #n ")" ::: "memory")
; #define PG8_BAR __builtin_amdgcn_s_barrier()
; #define PG8_SCHED __builtin_amdgcn_sched_barrier(0)
; template <class Epi, class Sched>
; DI void gemm_phase(LAS unsigned char* lds, const Gemm g, const Sched& S, const Epi& E, const int tid) {
;     ...
;             PG8_STAGE(PG8_SB(0, 1), b2 + hstepB, offB);
;             PG8_WAIT_V(6); PG8_BAR; PG8_MMA(1, 1, At, B1); PG8_BAR;
;             PG8_LDB(B0, 1, 0); PG8_SCHED; PG8_LDA(At, 1, 0); PG8_STAGE(PG8_SA(0, 1), a2 + hstepA, offA);
;             PG8_WAIT_L(8); PG8_BAR; PG8_WAIT_L(0); PG8_MMA(0, 0, At, B0); PG8_BAR; PG8_SCHED;
;             PG8_LDB(B1, 1, 1); PG8_STAGE(PG8_SB(1, 0), b3, offB);
;             PG8_BAR; PG8_WAIT_L(0); PG8_MMA(0, 1, At, B1); PG8_BAR;
;             PG8_LDA(At, 1, 1); PG8_STAGE(PG8_SA(1, 0), a3, offA);
	s_add_i32 s57, s57, s44
	v_lshl_add_u64 v[152:153], v[146:147], 0, s[24:25]
	s_mov_b32 m0, s57
	s_nop 0
	global_load_lds_dwordx4 v[152:153], off
	v_lshl_add_u64 v[152:153], v[146:147], 0, s[28:29]
	s_add_i32 m0, s57, 0x2000
	s_nop 0
	global_load_lds_dwordx4 v[152:153], off
	s_waitcnt vmcnt(6)
	s_barrier
	s_setprio 1
	v_mfma_f32_16x16x32_bf16 v[46:49], v[220:223], v[168:171], v[46:49]
	v_mfma_f32_16x16x32_bf16 v[42:45], v[228:231], v[168:171], v[42:45]
	v_mfma_f32_16x16x32_bf16 v[30:33], v[220:223], v[176:179], v[30:33]
	v_mfma_f32_16x16x32_bf16 v[26:29], v[228:231], v[176:179], v[26:29]
	v_mfma_f32_16x16x32_bf16 v[14:17], v[220:223], v[184:187], v[14:17]
	v_mfma_f32_16x16x32_bf16 v[10:13], v[228:231], v[184:187], v[10:13]
	v_mfma_f32_16x16x32_bf16 v[6:9], v[220:223], v[212:215], v[6:9]
	v_mfma_f32_16x16x32_bf16 v[2:5], v[228:231], v[212:215], v[2:5]
	v_mfma_f32_16x16x32_bf16 v[46:49], v[224:227], v[172:175], v[46:49]
	v_mfma_f32_16x16x32_bf16 v[42:45], v[244:247], v[172:175], v[42:45]
	v_mfma_f32_16x16x32_bf16 v[30:33], v[224:227], v[180:183], v[30:33]
	v_mfma_f32_16x16x32_bf16 v[26:29], v[244:247], v[180:183], v[26:29]
	v_mfma_f32_16x16x32_bf16 v[14:17], v[224:227], v[188:191], v[14:17]
	v_mfma_f32_16x16x32_bf16 v[10:13], v[244:247], v[188:191], v[10:13]
	v_mfma_f32_16x16x32_bf16 v[6:9], v[224:227], v[216:219], v[6:9]
	v_mfma_f32_16x16x32_bf16 v[2:5], v[244:247], v[216:219], v[2:5]
	s_setprio 0
	s_add_i32 s57, 0, 0x18000
	v_add_u32_e32 v164, s57, v143
	s_barrier
	ds_read_b128 v[152:155], v164
	ds_read_b128 v[156:159], v164 offset:1024
	ds_read_b128 v[160:163], v164 offset:2048
	ds_read_b128 v[164:167], v164 offset:3072
	s_mov_b32 m0, s47
	v_lshl_add_u64 v[220:221], v[192:193], 0, s[24:25]
	ds_read_b128 v[168:171], v145 offset:32768
	ds_read_b128 v[172:175], v145 offset:33792
	ds_read_b128 v[176:179], v145 offset:34816
	ds_read_b128 v[180:183], v145 offset:35840
	ds_read_b128 v[184:187], v145 offset:36864
	ds_read_b128 v[188:191], v145 offset:37888
	ds_read_b128 v[212:215], v145 offset:38912
	ds_read_b128 v[216:219], v145 offset:39936
	global_load_lds_dwordx4 v[220:221], off
	v_lshl_add_u64 v[220:221], v[192:193], 0, s[28:29]
	s_mov_b32 m0, s48
	s_nop 0
	global_load_lds_dwordx4 v[220:221], off
	s_waitcnt lgkmcnt(8)
	s_barrier
	s_waitcnt lgkmcnt(0)
	s_setprio 1
	s_waitcnt lgkmcnt(0)
	v_mfma_f32_16x16x32_bf16 v[126:129], v[152:155], v[168:171], v[126:129]
	v_mfma_f32_16x16x32_bf16 v[122:125], v[160:163], v[168:171], v[122:125]
	v_mfma_f32_16x16x32_bf16 v[118:121], v[152:155], v[176:179], v[118:121]
	v_mfma_f32_16x16x32_bf16 v[114:117], v[160:163], v[176:179], v[114:117]
	v_mfma_f32_16x16x32_bf16 v[102:105], v[152:155], v[184:187], v[102:105]
	v_mfma_f32_16x16x32_bf16 v[98:101], v[160:163], v[184:187], v[98:101]
	v_mfma_f32_16x16x32_bf16 v[86:89], v[152:155], v[212:215], v[86:89]
	v_mfma_f32_16x16x32_bf16 v[82:85], v[160:163], v[212:215], v[82:85]
	v_mfma_f32_16x16x32_bf16 v[126:129], v[156:159], v[172:175], v[126:129]
	v_mfma_f32_16x16x32_bf16 v[122:125], v[164:167], v[172:175], v[122:125]
	v_mfma_f32_16x16x32_bf16 v[118:121], v[156:159], v[180:183], v[118:121]
	v_mfma_f32_16x16x32_bf16 v[114:117], v[164:167], v[180:183], v[114:117]
	v_mfma_f32_16x16x32_bf16 v[102:105], v[156:159], v[188:191], v[102:105]
	v_mfma_f32_16x16x32_bf16 v[98:101], v[164:167], v[188:191], v[98:101]
	v_mfma_f32_16x16x32_bf16 v[86:89], v[156:159], v[216:219], v[86:89]
	v_mfma_f32_16x16x32_bf16 v[82:85], v[164:167], v[216:219], v[82:85]
	s_setprio 0
	s_barrier
	s_add_i32 s58, 0, 0x1c000
	s_add_i32 s57, s57, s44
	v_add_u32_e32 v198, s58, v143
	v_lshl_add_u64 v[248:249], v[146:147], 0, s[26:27]
	s_mov_b32 m0, s57
	ds_read_b128 v[220:223], v198
	ds_read_b128 v[224:227], v198 offset:1024
	ds_read_b128 v[228:231], v198 offset:2048
	ds_read_b128 v[244:247], v198 offset:3072
	global_load_lds_dwordx4 v[248:249], off
	v_lshl_add_u64 v[248:249], v[146:147], 0, s[36:37]
	s_add_i32 m0, s57, 0x2000
	s_nop 0
	global_load_lds_dwordx4 v[248:249], off
	s_barrier
	s_waitcnt lgkmcnt(0)
	s_setprio 1
	s_waitcnt lgkmcnt(0)
	v_mfma_f32_16x16x32_bf16 v[110:113], v[220:223], v[168:171], v[110:113]
	v_mfma_f32_16x16x32_bf16 v[106:109], v[228:231], v[168:171], v[106:109]
	v_mfma_f32_16x16x32_bf16 v[94:97], v[220:223], v[176:179], v[94:97]
	v_mfma_f32_16x16x32_bf16 v[90:93], v[228:231], v[176:179], v[90:93]
	v_mfma_f32_16x16x32_bf16 v[78:81], v[220:223], v[184:187], v[78:81]
	v_mfma_f32_16x16x32_bf16 v[74:77], v[228:231], v[184:187], v[74:77]
	v_mfma_f32_16x16x32_bf16 v[70:73], v[220:223], v[212:215], v[70:73]
	v_mfma_f32_16x16x32_bf16 v[66:69], v[228:231], v[212:215], v[66:69]
	v_mfma_f32_16x16x32_bf16 v[110:113], v[224:227], v[172:175], v[110:113]
	v_mfma_f32_16x16x32_bf16 v[106:109], v[244:247], v[172:175], v[106:109]
	v_mfma_f32_16x16x32_bf16 v[94:97], v[224:227], v[180:183], v[94:97]
	v_mfma_f32_16x16x32_bf16 v[90:93], v[244:247], v[180:183], v[90:93]
	v_mfma_f32_16x16x32_bf16 v[78:81], v[224:227], v[188:191], v[78:81]
	v_mfma_f32_16x16x32_bf16 v[74:77], v[244:247], v[188:191], v[74:77]
	v_mfma_f32_16x16x32_bf16 v[70:73], v[224:227], v[216:219], v[70:73]
	v_mfma_f32_16x16x32_bf16 v[66:69], v[244:247], v[216:219], v[66:69]
	s_setprio 0
	s_mov_b32 m0, s49
	v_lshl_add_u64 v[248:249], v[192:193], 0, s[26:27]
	s_barrier
	ds_read_b128 v[168:171], v145 offset:49152
	ds_read_b128 v[172:175], v145 offset:50176
	ds_read_b128 v[176:179], v145 offset:51200
	ds_read_b128 v[180:183], v145 offset:52224
	ds_read_b128 v[184:187], v145 offset:53248
	ds_read_b128 v[188:191], v145 offset:54272
	ds_read_b128 v[212:215], v145 offset:55296
	ds_read_b128 v[216:219], v145 offset:56320
	global_load_lds_dwordx4 v[248:249], off
	v_lshl_add_u64 v[192:193], v[192:193], 0, s[36:37]
	s_mov_b32 m0, s50
	s_nop 0
	global_load_lds_dwordx4 v[192:193], off
	s_barrier
; #define PG8_STAGE(bufoff, gbase, voff) do { _Pragma("unroll") for (int _i = 0; _i < 2; ++_i) \
;         __builtin_amdgcn_global_load_lds((const unsigned*)((const char*)(gbase) + (size_t)_i * p64##voff + (v##voff##_)), (LAS unsigned*)(lds + (bufoff) + ldsw + _i * 8192), 16, 0, 0); } while (0)
; #define PG8_MMA(ai, bj, At, Bt) do { __builtin_amdgcn_s_setprio(1); _Pragma("unroll") for (int m = 0; m < 4; ++m) _Pragma("unroll") for (int n = 0; n < 2; ++n) _Pragma("unroll") for (int k = 0; k < 2; ++k) \
;         acc[ai][bj][m][n] = __builtin_amdgcn_mfma_f32_16x16x32_bf16(Bt[n][k], At[m][k], acc[ai][bj][m][n], 0, 0, 0); __builtin_amdgcn_s_setprio(0); } while (0)
; #define PG8_WAIT_V(n) asm volatile("s_waitcnt vmcnt(" #n ")" ::: "memory")
; #define PG8_WAIT_L(n) asm volatile("s_waitcnt lgkmcnt(" #n ")" ::: "memory")
; #define PG8_BAR __builtin_amdgcn_s_barrier()
; #define PG8_SCHED __builtin_amdgcn_sched_barrier(0)
; template <class Epi, class Sched>
; DI void gemm_phase(LAS unsigned char* lds, const Gemm g, const Sched& S, const Epi& E, const int tid) {
;     ...
;         for (int t = 0; t < nt; t += 2) {
;             const bool last = (t == nt - 2);
;             const char* a1 = cA + (size_t)(t + 1) * kstep;
;             const char* a2 = last ? nA : cA + (size_t)(t + 2) * kstep; const char* b2 = last ? nB : cB + (size_t)(t + 2) * kstep;
;     ...
;             PG8_BAR; PG8_WAIT_L(0); PG8_MMA(1, 0, At, B0); PG8_BAR; PG8_SCHED;
;             PG8_STAGE(PG8_SB(1, 1), b3 + hstepB, offB);
;             PG8_WAIT_V(6); PG8_BAR; PG8_MMA(1, 1, At, B1); PG8_BAR;
	s_waitcnt lgkmcnt(0)
	s_setprio 1
	s_waitcnt lgkmcnt(0)
	v_mfma_f32_16x16x32_bf16 v[62:65], v[152:155], v[168:171], v[62:65]
	v_mfma_f32_16x16x32_bf16 v[58:61], v[160:163], v[168:171], v[58:61]
	v_mfma_f32_16x16x32_bf16 v[54:57], v[152:155], v[176:179], v[54:57]
	v_mfma_f32_16x16x32_bf16 v[50:53], v[160:163], v[176:179], v[50:53]
	v_mfma_f32_16x16x32_bf16 v[38:41], v[152:155], v[184:187], v[38:41]
	v_mfma_f32_16x16x32_bf16 v[34:37], v[160:163], v[184:187], v[34:37]
	v_mfma_f32_16x16x32_bf16 v[22:25], v[152:155], v[212:215], v[22:25]
	v_mfma_f32_16x16x32_bf16 v[18:21], v[160:163], v[212:215], v[18:21]
	v_mfma_f32_16x16x32_bf16 v[62:65], v[156:159], v[172:175], v[62:65]
	v_mfma_f32_16x16x32_bf16 v[58:61], v[164:167], v[172:175], v[58:61]
	v_mfma_f32_16x16x32_bf16 v[54:57], v[156:159], v[180:183], v[54:57]
	v_mfma_f32_16x16x32_bf16 v[50:53], v[164:167], v[180:183], v[50:53]
	v_mfma_f32_16x16x32_bf16 v[38:41], v[156:159], v[188:191], v[38:41]
	v_mfma_f32_16x16x32_bf16 v[34:37], v[164:167], v[188:191], v[34:37]
	v_mfma_f32_16x16x32_bf16 v[22:25], v[156:159], v[216:219], v[22:25]
	v_mfma_f32_16x16x32_bf16 v[18:21], v[164:167], v[216:219], v[18:21]
	s_setprio 0
	s_barrier
	s_add_i32 s57, s58, s44
	v_lshl_add_u64 v[152:153], v[146:147], 0, s[34:35]
	s_mov_b32 m0, s57
	v_lshl_add_u64 v[146:147], v[146:147], 0, s[18:19]
	global_load_lds_dwordx4 v[152:153], off
	s_add_i32 m0, s57, 0x2000
	s_nop 0
	global_load_lds_dwordx4 v[146:147], off
	s_waitcnt vmcnt(6)
	s_barrier
	s_setprio 1
	v_mfma_f32_16x16x32_bf16 v[46:49], v[220:223], v[168:171], v[46:49]
	v_mfma_f32_16x16x32_bf16 v[42:45], v[228:231], v[168:171], v[42:45]
	v_mfma_f32_16x16x32_bf16 v[30:33], v[220:223], v[176:179], v[30:33]
	v_mfma_f32_16x16x32_bf16 v[26:29], v[228:231], v[176:179], v[26:29]
	v_mfma_f32_16x16x32_bf16 v[14:17], v[220:223], v[184:187], v[14:17]
	v_mfma_f32_16x16x32_bf16 v[10:13], v[228:231], v[184:187], v[10:13]
	v_mfma_f32_16x16x32_bf16 v[6:9], v[220:223], v[212:215], v[6:9]
	v_mfma_f32_16x16x32_bf16 v[2:5], v[228:231], v[212:215], v[2:5]
	v_mfma_f32_16x16x32_bf16 v[46:49], v[224:227], v[172:175], v[46:49]
	v_mfma_f32_16x16x32_bf16 v[42:45], v[244:247], v[172:175], v[42:45]
	v_mfma_f32_16x16x32_bf16 v[30:33], v[224:227], v[180:183], v[30:33]
	v_mfma_f32_16x16x32_bf16 v[26:29], v[244:247], v[180:183], v[26:29]
	v_mfma_f32_16x16x32_bf16 v[14:17], v[224:227], v[188:191], v[14:17]
	v_mfma_f32_16x16x32_bf16 v[10:13], v[244:247], v[188:191], v[10:13]
	v_mfma_f32_16x16x32_bf16 v[6:9], v[224:227], v[216:219], v[6:9]
	v_mfma_f32_16x16x32_bf16 v[2:5], v[244:247], v[216:219], v[2:5]
	s_setprio 0
	s_add_i32 s56, s56, 2
	s_add_u32 s40, s40, 0x100
	s_addc_u32 s41, s41, 0
	s_add_u32 s42, s42, 0x100
	s_addc_u32 s43, s43, 0
	s_cmp_gt_u32 s56, 13
	s_barrier
	s_cbranch_scc0 .LBB0_556
; DI unsigned pk2(float lo, float hi) { f32x2 v = {lo, hi}; bf2_t b = __builtin_convertvector(v, bf2_t); return __builtin_bit_cast(unsigned, b); }
; #define PG8_WAIT_V(n) asm volatile("s_waitcnt vmcnt(" #n ")" ::: "memory")
; #define PG8_BAR __builtin_amdgcn_s_barrier()
;     DI void operator()(const f32x4 (&acc)[2][2][4][2], const Unit& u, int wr, int wc, int fr, int fq) const {
;         const int row0 = u.pm * BM + wr * 64 + fr, col0 = u.pn * BM + wc * 32 + 8 * fq;
; #pragma unroll
;         for (int ai = 0; ai < 2; ++ai)
; #pragma unroll
;             for (int m = 0; m < 4; ++m) { bf16_t* rowp = O + (size_t)(row0 + ai * HALF + m * 16) * ldc + col0;
; #pragma unroll
;                 for (int bj = 0; bj < 2; ++bj) { f32x4 v0 = acc[ai][bj][m][0], v1 = acc[ai][bj][m][1];
;                     if (ACT == 1) {
; #pragma unroll
;                         for (int j = 0; j < 4; ++j) { float a = fmaxf(v0[j], 0.f), b = fmaxf(v1[j], 0.f); v0[j] = a * a; v1[j] = b * b; } }
;                     u32x4 w; w.x = pk2(v0[0], v0[1]); w.y = pk2(v0[2], v0[3]); w.z = pk2(v1[0], v1[1]); w.w = pk2(v1[2], v1[3]);
;                     *(u32x4*)(rowp + bj * HALF) = w; } }
; template <class Epi, class Sched>
; DI void gemm_phase(LAS unsigned char* lds, const Gemm g, const Sched& S, const Epi& E, const int tid) {
;     ...
;         cur = nxt; cA = nA; cB = nB; ++ui;
;     }
;     PG8_WAIT_V(0);
;     if (wr == 0) PG8_BAR;
	v_lshl_add_u32 v156, s53, 8, v142
	v_lshl_or_b32 v146, s52, 8, v144
	v_ashrrev_i32_e32 v147, 31, v146
	v_mov_b64_e32 v[152:153], s[68:69]
	s_movk_i32 s1, 0x1600
	v_cvt_pk_bf16_f32 v70, v70, v71
	v_cvt_pk_bf16_f32 v71, v72, v73
	v_cvt_pk_bf16_f32 v72, v66, v67
	v_add_u32_e32 v66, 0x80, v156
	v_mad_i64_i32 v[154:155], s[40:41], v156, s1, v[152:153]
	v_lshlrev_b64 v[146:147], 1, v[146:147]
	v_cvt_pk_bf16_f32 v110, v110, v111
	v_cvt_pk_bf16_f32 v111, v112, v113
	v_cvt_pk_bf16_f32 v112, v106, v107
	v_or_b32_e32 v106, 16, v156
	v_mad_i64_i32 v[66:67], s[40:41], v66, s1, v[152:153]
	v_cvt_pk_bf16_f32 v46, v46, v47
	v_cvt_pk_bf16_f32 v47, v48, v49
	v_cvt_pk_bf16_f32 v48, v42, v43
	v_add_u32_e32 v42, 0x90, v156
	v_lshl_add_u64 v[154:155], v[154:155], 0, v[146:147]
	v_cvt_pk_bf16_f32 v113, v108, v109
	v_mad_i64_i32 v[106:107], s[40:41], v106, s1, v[152:153]
	v_cvt_pk_bf16_f32 v94, v94, v95
	v_cvt_pk_bf16_f32 v95, v96, v97
	v_cvt_pk_bf16_f32 v96, v90, v91
	v_or_b32_e32 v90, 32, v156
	v_lshl_add_u64 v[66:67], v[66:67], 0, v[146:147]
	v_cvt_pk_bf16_f32 v49, v44, v45
	v_mad_i64_i32 v[42:43], s[40:41], v42, s1, v[152:153]
	v_cvt_pk_bf16_f32 v30, v30, v31
	v_cvt_pk_bf16_f32 v31, v32, v33
	v_cvt_pk_bf16_f32 v32, v26, v27
	v_add_u32_e32 v26, 0xa0, v156
	global_store_dwordx4 v[154:155], v[110:113], off offset:256 nt
	v_cvt_pk_bf16_f32 v97, v92, v93
	v_mad_i64_i32 v[90:91], s[40:41], v90, s1, v[152:153]
	v_lshl_add_u64 v[110:111], v[106:107], 0, v[146:147]
	v_cvt_pk_bf16_f32 v78, v78, v79
	v_cvt_pk_bf16_f32 v79, v80, v81
	v_cvt_pk_bf16_f32 v80, v74, v75
	v_or_b32_e32 v74, 48, v156
	global_store_dwordx4 v[66:67], v[46:49], off offset:256 nt
	v_cvt_pk_bf16_f32 v33, v28, v29
	v_mad_i64_i32 v[26:27], s[40:41], v26, s1, v[152:153]
	v_lshl_add_u64 v[46:47], v[42:43], 0, v[146:147]
	v_cvt_pk_bf16_f32 v14, v14, v15
	v_cvt_pk_bf16_f32 v15, v16, v17
	v_cvt_pk_bf16_f32 v16, v10, v11
	v_add_u32_e32 v10, 0xb0, v156
	global_store_dwordx4 v[110:111], v[94:97], off offset:256 nt
	v_cvt_pk_bf16_f32 v81, v76, v77
	v_mad_i64_i32 v[74:75], s[40:41], v74, s1, v[152:153]
	v_lshl_add_u64 v[94:95], v[90:91], 0, v[146:147]
	global_store_dwordx4 v[46:47], v[30:33], off offset:256 nt
	v_cvt_pk_bf16_f32 v17, v12, v13
	v_mad_i64_i32 v[10:11], s[40:41], v10, s1, v[152:153]
	v_lshl_add_u64 v[30:31], v[26:27], 0, v[146:147]
	v_cvt_pk_bf16_f32 v126, v126, v127
	v_cvt_pk_bf16_f32 v127, v128, v129
	v_cvt_pk_bf16_f32 v128, v122, v123
	v_cvt_pk_bf16_f32 v129, v124, v125
	v_cvt_pk_bf16_f32 v106, v118, v119
	v_cvt_pk_bf16_f32 v107, v120, v121
	v_cvt_pk_bf16_f32 v108, v114, v115
	v_cvt_pk_bf16_f32 v109, v116, v117
	v_cvt_pk_bf16_f32 v90, v102, v103
	v_cvt_pk_bf16_f32 v91, v104, v105
	v_cvt_pk_bf16_f32 v92, v98, v99
	v_cvt_pk_bf16_f32 v93, v100, v101
	global_store_dwordx4 v[94:95], v[78:81], off offset:256 nt
	v_cvt_pk_bf16_f32 v76, v82, v83
	v_cvt_pk_bf16_f32 v77, v84, v85
	v_lshl_add_u64 v[78:79], v[74:75], 0, v[146:147]
	v_cvt_pk_bf16_f32 v74, v86, v87
	v_cvt_pk_bf16_f32 v75, v88, v89
	v_cvt_pk_bf16_f32 v73, v68, v69
	v_cvt_pk_bf16_f32 v62, v62, v63
	v_cvt_pk_bf16_f32 v63, v64, v65
	v_cvt_pk_bf16_f32 v64, v58, v59
	v_cvt_pk_bf16_f32 v65, v60, v61
	v_cvt_pk_bf16_f32 v42, v54, v55
	v_cvt_pk_bf16_f32 v43, v56, v57
	v_cvt_pk_bf16_f32 v44, v50, v51
	v_cvt_pk_bf16_f32 v45, v52, v53
	v_cvt_pk_bf16_f32 v26, v38, v39
	v_cvt_pk_bf16_f32 v27, v40, v41
	v_cvt_pk_bf16_f32 v28, v34, v35
	v_cvt_pk_bf16_f32 v29, v36, v37
	global_store_dwordx4 v[30:31], v[14:17], off offset:256 nt
	v_cvt_pk_bf16_f32 v12, v18, v19
	v_cvt_pk_bf16_f32 v13, v20, v21
	v_lshl_add_u64 v[14:15], v[10:11], 0, v[146:147]
	v_cvt_pk_bf16_f32 v10, v22, v23
	v_cvt_pk_bf16_f32 v11, v24, v25
	v_cvt_pk_bf16_f32 v6, v6, v7
	v_cvt_pk_bf16_f32 v7, v8, v9
	v_cvt_pk_bf16_f32 v8, v2, v3
	v_cvt_pk_bf16_f32 v9, v4, v5
	s_and_b64 vcc, exec, s[38:39]
	s_mov_b32 s52, s0
	s_mov_b32 s53, s4
	s_mov_b64 s[42:43], s[8:9]
	s_mov_b64 s[40:41], s[6:7]
	global_store_dwordx4 v[154:155], v[126:129], off nt
	global_store_dwordx4 v[110:111], v[106:109], off nt
	global_store_dwordx4 v[94:95], v[90:93], off nt
	global_store_dwordx4 v[78:79], v[74:77], off nt
	global_store_dwordx4 v[78:79], v[70:73], off offset:256 nt
	global_store_dwordx4 v[66:67], v[62:65], off nt
	global_store_dwordx4 v[46:47], v[42:45], off nt
	global_store_dwordx4 v[30:31], v[26:29], off nt
	global_store_dwordx4 v[14:15], v[10:13], off nt
	global_store_dwordx4 v[14:15], v[6:9], off offset:256 nt
	s_cbranch_vccz .LBB0_553
	s_waitcnt vmcnt(0)
	s_cmpk_gt_u32 s2, 0xff
	s_cbranch_scc1 .LBB0_560
	s_barrier

; #define PG8_STAGE(bufoff, gbase, voff) do { _Pragma("unroll") for (int _i = 0; _i < 2; ++_i) \
;         __builtin_amdgcn_global_load_lds((const unsigned*)((const char*)(gbase) + (size_t)_i * p64##voff + (v##voff##_)), (LAS unsigned*)(lds + (bufoff) + ldsw + _i * 8192), 16, 0, 0); } while (0)
; #define PG8_LDA(dst, b, h) do { _Pragma("unroll") for (int m = 0; m < 4; ++m) _Pragma("unroll") for (int k = 0; k < 2; ++k) dst[m][k] = *(const LAS bf16x8*)(lds + PG8_SA(b, h) + aoff + m * 2048 + k * 1024); } while (0)
; #define PG8_LDB(dst, b, h) do { _Pragma("unroll") for (int n = 0; n < 2; ++n) _Pragma("unroll") for (int k = 0; k < 2; ++k) dst[n][k] = *(const LAS bf16x8*)(lds + PG8_SB(b, h) + boff + n * 2048 + k * 1024); } while (0)
; #define PG8_MMA(ai, bj, At, Bt) do { __builtin_amdgcn_s_setprio(1); _Pragma("unroll") for (int m = 0; m < 4; ++m) _Pragma("unroll") for (int n = 0; n < 2; ++n) _Pragma("unroll") for (int k = 0; k < 2; ++k) \
;         acc[ai][bj][m][n] = __builtin_amdgcn_mfma_f32_16x16x32_bf16(Bt[n][k], At[m][k], acc[ai][bj][m][n], 0, 0, 0); __builtin_amdgcn_s_setprio(0); } while (0)
; #define PG8_WAIT_L(n) asm volatile("s_waitcnt lgkmcnt(" #n ")" ::: "memory")
; #define PG8_BAR __builtin_amdgcn_s_barrier()
; #define PG8_SCHED __builtin_amdgcn_sched_barrier(0)
; template <class Epi, class Sched>
; DI void gemm_phase(LAS unsigned char* lds, const Gemm g, const Sched& S, const Epi& E, const int tid) {
;     ...
;         for (int t = 0; t < nt; t += 2) {
;             const bool last = (t == nt - 2);
;             const char* a1 = cA + (size_t)(t + 1) * kstep;
;             const char* a2 = last ? nA : cA + (size_t)(t + 2) * kstep; const char* b2 = last ? nB : cB + (size_t)(t + 2) * kstep;
;             const char* a3 = a2 + kstep; const char* b3 = b2 + kstep;
;             PG8_LDB(B0, 0, 0); PG8_SCHED; PG8_LDA(At, 0, 0); PG8_STAGE(PG8_SA(1, 1), a1 + hstepA, offA);
;             PG8_WAIT_L(8); PG8_BAR; PG8_WAIT_L(0); PG8_MMA(0, 0, At, B0); PG8_BAR; PG8_SCHED;
;             PG8_LDB(B1, 0, 1); PG8_STAGE(PG8_SB(0, 0), b2, offB);
;             PG8_BAR; PG8_WAIT_L(0); PG8_MMA(0, 1, At, B1); PG8_BAR;
;             PG8_LDA(At, 0, 1); PG8_STAGE(PG8_SA(0, 0), a2, offA);
;             PG8_BAR; PG8_WAIT_L(0); PG8_MMA(1, 0, At, B0); PG8_BAR; PG8_SCHED;
.LBB0_568:
	s_add_u32 s59, s40, 0xfffc0080
	s_addc_u32 s60, s41, -1
	s_add_i32 s64, 0, 0x10000
	v_add_u32_e32 v146, s64, v143
	ds_read_b128 v[152:155], v146
	ds_read_b128 v[156:159], v146 offset:1024
	ds_read_b128 v[160:163], v146 offset:2048
	ds_read_b128 v[164:167], v146 offset:3072
	s_cmp_eq_u32 s58, 12
	s_cselect_b32 s61, s5, s60
	s_cselect_b32 s60, s56, s59
	s_cselect_b32 s63, s1, s43
	s_cselect_b32 s62, s57, s42
	v_lshl_add_u64 v[146:147], s[40:41], 0, v[132:133]
	s_add_i32 m0, s47, 0xc000
	ds_read_b128 v[168:171], v145
	ds_read_b128 v[172:175], v145 offset:1024
	ds_read_b128 v[176:179], v145 offset:2048
	ds_read_b128 v[180:183], v145 offset:3072
	ds_read_b128 v[184:187], v145 offset:4096
	ds_read_b128 v[188:191], v145 offset:5120
	ds_read_b128 v[212:215], v145 offset:6144
	ds_read_b128 v[216:219], v145 offset:7168
	global_load_lds_dwordx4 v[146:147], off
	v_lshl_add_u64 v[146:147], v[146:147], 0, s[10:11]
	s_add_i32 m0, s47, 0xe000
	s_nop 0
	global_load_lds_dwordx4 v[146:147], off
	s_waitcnt lgkmcnt(8)
	s_barrier
	s_waitcnt lgkmcnt(0)
	s_setprio 1
	s_waitcnt lgkmcnt(0)
	v_mfma_f32_16x16x32_bf16 v[126:129], v[152:155], v[168:171], v[126:129]
	v_mfma_f32_16x16x32_bf16 v[122:125], v[160:163], v[168:171], v[122:125]
	v_mfma_f32_16x16x32_bf16 v[118:121], v[152:155], v[176:179], v[118:121]
	v_mfma_f32_16x16x32_bf16 v[114:117], v[160:163], v[176:179], v[114:117]
	v_mfma_f32_16x16x32_bf16 v[102:105], v[152:155], v[184:187], v[102:105]
	v_mfma_f32_16x16x32_bf16 v[98:101], v[160:163], v[184:187], v[98:101]
	v_mfma_f32_16x16x32_bf16 v[86:89], v[152:155], v[212:215], v[86:89]
	v_mfma_f32_16x16x32_bf16 v[82:85], v[160:163], v[212:215], v[82:85]
	v_mfma_f32_16x16x32_bf16 v[126:129], v[156:159], v[172:175], v[126:129]
	v_mfma_f32_16x16x32_bf16 v[122:125], v[164:167], v[172:175], v[122:125]
	v_mfma_f32_16x16x32_bf16 v[118:121], v[156:159], v[180:183], v[118:121]
	v_mfma_f32_16x16x32_bf16 v[114:117], v[164:167], v[180:183], v[114:117]
	v_mfma_f32_16x16x32_bf16 v[102:105], v[156:159], v[188:191], v[102:105]
	v_mfma_f32_16x16x32_bf16 v[98:101], v[164:167], v[188:191], v[98:101]
	v_mfma_f32_16x16x32_bf16 v[86:89], v[156:159], v[216:219], v[86:89]
	v_mfma_f32_16x16x32_bf16 v[82:85], v[164:167], v[216:219], v[82:85]
	s_setprio 0
	s_barrier
	s_add_i32 s59, 0, 0x14000
	v_add_u32_e32 v146, s59, v143
	ds_read_b128 v[220:223], v146
	ds_read_b128 v[224:227], v146 offset:1024
	ds_read_b128 v[228:231], v146 offset:2048
	ds_read_b128 v[244:247], v146 offset:3072
	v_lshl_add_u64 v[146:147], s[62:63], 0, v[0:1]
	s_add_i32 s62, s64, s46
	s_mov_b32 m0, s62
	v_lshl_add_u64 v[192:193], v[146:147], 0, s[10:11]
	global_load_lds_dwordx4 v[146:147], off
	s_add_i32 m0, s62, 0x2000
	s_nop 0
	global_load_lds_dwordx4 v[192:193], off
	s_barrier
	s_waitcnt lgkmcnt(0)
	s_setprio 1
	s_waitcnt lgkmcnt(0)
	v_mfma_f32_16x16x32_bf16 v[110:113], v[220:223], v[168:171], v[110:113]
	v_mfma_f32_16x16x32_bf16 v[106:109], v[228:231], v[168:171], v[106:109]
	v_mfma_f32_16x16x32_bf16 v[94:97], v[220:223], v[176:179], v[94:97]
	v_mfma_f32_16x16x32_bf16 v[90:93], v[228:231], v[176:179], v[90:93]
	v_mfma_f32_16x16x32_bf16 v[78:81], v[220:223], v[184:187], v[78:81]
	v_mfma_f32_16x16x32_bf16 v[74:77], v[228:231], v[184:187], v[74:77]
	v_mfma_f32_16x16x32_bf16 v[70:73], v[220:223], v[212:215], v[70:73]
	v_mfma_f32_16x16x32_bf16 v[66:69], v[228:231], v[212:215], v[66:69]
	v_mfma_f32_16x16x32_bf16 v[110:113], v[224:227], v[172:175], v[110:113]
	v_mfma_f32_16x16x32_bf16 v[106:109], v[244:247], v[172:175], v[106:109]
	v_mfma_f32_16x16x32_bf16 v[94:97], v[224:227], v[180:183], v[94:97]
	v_mfma_f32_16x16x32_bf16 v[90:93], v[244:247], v[180:183], v[90:93]
	v_mfma_f32_16x16x32_bf16 v[78:81], v[224:227], v[188:191], v[78:81]
	v_mfma_f32_16x16x32_bf16 v[74:77], v[244:247], v[188:191], v[74:77]
	v_mfma_f32_16x16x32_bf16 v[70:73], v[224:227], v[216:219], v[70:73]
	v_mfma_f32_16x16x32_bf16 v[66:69], v[244:247], v[216:219], v[66:69]
	s_setprio 0
	s_mov_b32 m0, s47
	v_lshl_add_u64 v[192:193], s[60:61], 0, v[130:131]
	s_barrier
	ds_read_b128 v[168:171], v145 offset:16384
	ds_read_b128 v[172:175], v145 offset:17408
	ds_read_b128 v[176:179], v145 offset:18432
	ds_read_b128 v[180:183], v145 offset:19456
	ds_read_b128 v[184:187], v145 offset:20480
	ds_read_b128 v[188:191], v145 offset:21504
	ds_read_b128 v[212:215], v145 offset:22528
	ds_read_b128 v[216:219], v145 offset:23552
	global_load_lds_dwordx4 v[192:193], off
	v_lshl_add_u64 v[248:249], v[192:193], 0, s[10:11]
	s_mov_b32 m0, s48
	s_nop 0
	global_load_lds_dwordx4 v[248:249], off
	s_barrier
	s_waitcnt lgkmcnt(0)
	s_setprio 1
	s_waitcnt lgkmcnt(0)
	v_mfma_f32_16x16x32_bf16 v[62:65], v[152:155], v[168:171], v[62:65]
	v_mfma_f32_16x16x32_bf16 v[58:61], v[160:163], v[168:171], v[58:61]
	v_mfma_f32_16x16x32_bf16 v[54:57], v[152:155], v[176:179], v[54:57]
	v_mfma_f32_16x16x32_bf16 v[50:53], v[160:163], v[176:179], v[50:53]
	v_mfma_f32_16x16x32_bf16 v[38:41], v[152:155], v[184:187], v[38:41]
	v_mfma_f32_16x16x32_bf16 v[34:37], v[160:163], v[184:187], v[34:37]
	v_mfma_f32_16x16x32_bf16 v[22:25], v[152:155], v[212:215], v[22:25]
	v_mfma_f32_16x16x32_bf16 v[18:21], v[160:163], v[212:215], v[18:21]
	v_mfma_f32_16x16x32_bf16 v[62:65], v[156:159], v[172:175], v[62:65]
	v_mfma_f32_16x16x32_bf16 v[58:61], v[164:167], v[172:175], v[58:61]
	v_mfma_f32_16x16x32_bf16 v[54:57], v[156:159], v[180:183], v[54:57]
	v_mfma_f32_16x16x32_bf16 v[50:53], v[164:167], v[180:183], v[50:53]
	v_mfma_f32_16x16x32_bf16 v[38:41], v[156:159], v[188:191], v[38:41]
	v_mfma_f32_16x16x32_bf16 v[34:37], v[164:167], v[188:191], v[34:37]
	v_mfma_f32_16x16x32_bf16 v[22:25], v[156:159], v[216:219], v[22:25]
	v_mfma_f32_16x16x32_bf16 v[18:21], v[164:167], v[216:219], v[18:21]
	s_setprio 0
	s_barrier
; #define PG8_STAGE(bufoff, gbase, voff) do { _Pragma("unroll") for (int _i = 0; _i < 2; ++_i) \
;         __builtin_amdgcn_global_load_lds((const unsigned*)((const char*)(gbase) + (size_t)_i * p64##voff + (v##voff##_)), (LAS unsigned*)(lds + (bufoff) + ldsw + _i * 8192), 16, 0, 0); } while (0)
; #define PG8_LDA(dst, b, h) do { _Pragma("unroll") for (int m = 0; m < 4; ++m) _Pragma("unroll") for (int k = 0; k < 2; ++k) dst[m][k] = *(const LAS bf16x8*)(lds + PG8_SA(b, h) + aoff + m * 2048 + k * 1024); } while (0)
; #define PG8_LDB(dst, b, h) do { _Pragma("unroll") for (int n = 0; n < 2; ++n) _Pragma("unroll") for (int k = 0; k < 2; ++k) dst[n][k] = *(const LAS bf16x8*)(lds + PG8_SB(b, h) + boff + n * 2048 + k * 1024); } while (0)
; #define PG8_MMA(ai, bj, At, Bt) do { __builtin_amdgcn_s_setprio(1); _Pragma("unroll") for (int m = 0; m < 4; ++m) _Pragma("unroll") for (int n = 0; n < 2; ++n) _Pragma("unroll") for (int k = 0; k < 2; ++k) \
;         acc[ai][bj][m][n] = __builtin_amdgcn_mfma_f32_16x16x32_bf16(Bt[n][k], At[m][k], acc[ai][bj][m][n], 0, 0, 0); __builtin_amdgcn_s_setprio(0); } while (0)
; #define PG8_WAIT_V(n) asm volatile("s_waitcnt vmcnt(" #n ")" ::: "memory")
; #define PG8_WAIT_L(n) asm volatile("s_waitcnt lgkmcnt(" #n ")" ::: "memory")
; #define PG8_BAR __builtin_amdgcn_s_barrier()
; #define PG8_SCHED __builtin_amdgcn_sched_barrier(0)
; template <class Epi, class Sched>
; DI void gemm_phase(LAS unsigned char* lds, const Gemm g, const Sched& S, const Epi& E, const int tid) {
;     ...
;             PG8_STAGE(PG8_SB(0, 1), b2 + hstepB, offB);
;             PG8_WAIT_V(6); PG8_BAR; PG8_MMA(1, 1, At, B1); PG8_BAR;
;             PG8_LDB(B0, 1, 0); PG8_SCHED; PG8_LDA(At, 1, 0); PG8_STAGE(PG8_SA(0, 1), a2 + hstepA, offA);
;             PG8_WAIT_L(8); PG8_BAR; PG8_WAIT_L(0); PG8_MMA(0, 0, At, B0); PG8_BAR; PG8_SCHED;
;             PG8_LDB(B1, 1, 1); PG8_STAGE(PG8_SB(1, 0), b3, offB);
;             PG8_BAR; PG8_WAIT_L(0); PG8_MMA(0, 1, At, B1); PG8_BAR;
;             PG8_LDA(At, 1, 1); PG8_STAGE(PG8_SA(1, 0), a3, offA);
	s_add_i32 s59, s59, s46
	v_lshl_add_u64 v[152:153], v[146:147], 0, s[24:25]
	s_mov_b32 m0, s59
	s_nop 0
	global_load_lds_dwordx4 v[152:153], off
	v_lshl_add_u64 v[152:153], v[146:147], 0, s[28:29]
	s_add_i32 m0, s59, 0x2000
	s_nop 0
	global_load_lds_dwordx4 v[152:153], off
	s_waitcnt vmcnt(6)
	s_barrier
	s_setprio 1
	v_mfma_f32_16x16x32_bf16 v[46:49], v[220:223], v[168:171], v[46:49]
	v_mfma_f32_16x16x32_bf16 v[42:45], v[228:231], v[168:171], v[42:45]
	v_mfma_f32_16x16x32_bf16 v[30:33], v[220:223], v[176:179], v[30:33]
	v_mfma_f32_16x16x32_bf16 v[26:29], v[228:231], v[176:179], v[26:29]
	v_mfma_f32_16x16x32_bf16 v[14:17], v[220:223], v[184:187], v[14:17]
	v_mfma_f32_16x16x32_bf16 v[10:13], v[228:231], v[184:187], v[10:13]
	v_mfma_f32_16x16x32_bf16 v[6:9], v[220:223], v[212:215], v[6:9]
	v_mfma_f32_16x16x32_bf16 v[2:5], v[228:231], v[212:215], v[2:5]
	v_mfma_f32_16x16x32_bf16 v[46:49], v[224:227], v[172:175], v[46:49]
	v_mfma_f32_16x16x32_bf16 v[42:45], v[244:247], v[172:175], v[42:45]
	v_mfma_f32_16x16x32_bf16 v[30:33], v[224:227], v[180:183], v[30:33]
	v_mfma_f32_16x16x32_bf16 v[26:29], v[244:247], v[180:183], v[26:29]
	v_mfma_f32_16x16x32_bf16 v[14:17], v[224:227], v[188:191], v[14:17]
	v_mfma_f32_16x16x32_bf16 v[10:13], v[244:247], v[188:191], v[10:13]
	v_mfma_f32_16x16x32_bf16 v[6:9], v[224:227], v[216:219], v[6:9]
	v_mfma_f32_16x16x32_bf16 v[2:5], v[244:247], v[216:219], v[2:5]
	s_setprio 0
	s_add_i32 s59, 0, 0x18000
	v_add_u32_e32 v164, s59, v143
	s_barrier
	ds_read_b128 v[152:155], v164
	ds_read_b128 v[156:159], v164 offset:1024
	ds_read_b128 v[160:163], v164 offset:2048
	ds_read_b128 v[164:167], v164 offset:3072
	s_mov_b32 m0, s49
	v_lshl_add_u64 v[220:221], v[192:193], 0, s[24:25]
	ds_read_b128 v[168:171], v145 offset:32768
	ds_read_b128 v[172:175], v145 offset:33792
	ds_read_b128 v[176:179], v145 offset:34816
	ds_read_b128 v[180:183], v145 offset:35840
	ds_read_b128 v[184:187], v145 offset:36864
	ds_read_b128 v[188:191], v145 offset:37888
	ds_read_b128 v[212:215], v145 offset:38912
	ds_read_b128 v[216:219], v145 offset:39936
	global_load_lds_dwordx4 v[220:221], off
	v_lshl_add_u64 v[220:221], v[192:193], 0, s[28:29]
	s_mov_b32 m0, s50
	s_nop 0
	global_load_lds_dwordx4 v[220:221], off
	s_waitcnt lgkmcnt(8)
	s_barrier
	s_waitcnt lgkmcnt(0)
	s_setprio 1
	s_waitcnt lgkmcnt(0)
	v_mfma_f32_16x16x32_bf16 v[126:129], v[152:155], v[168:171], v[126:129]
	v_mfma_f32_16x16x32_bf16 v[122:125], v[160:163], v[168:171], v[122:125]
	v_mfma_f32_16x16x32_bf16 v[118:121], v[152:155], v[176:179], v[118:121]
	v_mfma_f32_16x16x32_bf16 v[114:117], v[160:163], v[176:179], v[114:117]
	v_mfma_f32_16x16x32_bf16 v[102:105], v[152:155], v[184:187], v[102:105]
	v_mfma_f32_16x16x32_bf16 v[98:101], v[160:163], v[184:187], v[98:101]
	v_mfma_f32_16x16x32_bf16 v[86:89], v[152:155], v[212:215], v[86:89]
	v_mfma_f32_16x16x32_bf16 v[82:85], v[160:163], v[212:215], v[82:85]
	v_mfma_f32_16x16x32_bf16 v[126:129], v[156:159], v[172:175], v[126:129]
	v_mfma_f32_16x16x32_bf16 v[122:125], v[164:167], v[172:175], v[122:125]
	v_mfma_f32_16x16x32_bf16 v[118:121], v[156:159], v[180:183], v[118:121]
	v_mfma_f32_16x16x32_bf16 v[114:117], v[164:167], v[180:183], v[114:117]
	v_mfma_f32_16x16x32_bf16 v[102:105], v[156:159], v[188:191], v[102:105]
	v_mfma_f32_16x16x32_bf16 v[98:101], v[164:167], v[188:191], v[98:101]
	v_mfma_f32_16x16x32_bf16 v[86:89], v[156:159], v[216:219], v[86:89]
	v_mfma_f32_16x16x32_bf16 v[82:85], v[164:167], v[216:219], v[82:85]
	s_setprio 0
	s_barrier
	s_add_i32 s60, 0, 0x1c000
	s_add_i32 s59, s59, s46
	v_add_u32_e32 v198, s60, v143
	v_lshl_add_u64 v[248:249], v[146:147], 0, s[26:27]
	s_mov_b32 m0, s59
	ds_read_b128 v[220:223], v198
	ds_read_b128 v[224:227], v198 offset:1024
	ds_read_b128 v[228:231], v198 offset:2048
	ds_read_b128 v[244:247], v198 offset:3072
	global_load_lds_dwordx4 v[248:249], off
	v_lshl_add_u64 v[248:249], v[146:147], 0, s[36:37]
	s_add_i32 m0, s59, 0x2000
	s_nop 0
	global_load_lds_dwordx4 v[248:249], off
	s_barrier
	s_waitcnt lgkmcnt(0)
	s_setprio 1
	s_waitcnt lgkmcnt(0)
	v_mfma_f32_16x16x32_bf16 v[110:113], v[220:223], v[168:171], v[110:113]
	v_mfma_f32_16x16x32_bf16 v[106:109], v[228:231], v[168:171], v[106:109]
	v_mfma_f32_16x16x32_bf16 v[94:97], v[220:223], v[176:179], v[94:97]
	v_mfma_f32_16x16x32_bf16 v[90:93], v[228:231], v[176:179], v[90:93]
	v_mfma_f32_16x16x32_bf16 v[78:81], v[220:223], v[184:187], v[78:81]
	v_mfma_f32_16x16x32_bf16 v[74:77], v[228:231], v[184:187], v[74:77]
	v_mfma_f32_16x16x32_bf16 v[70:73], v[220:223], v[212:215], v[70:73]
	v_mfma_f32_16x16x32_bf16 v[66:69], v[228:231], v[212:215], v[66:69]
	v_mfma_f32_16x16x32_bf16 v[110:113], v[224:227], v[172:175], v[110:113]
	v_mfma_f32_16x16x32_bf16 v[106:109], v[244:247], v[172:175], v[106:109]
	v_mfma_f32_16x16x32_bf16 v[94:97], v[224:227], v[180:183], v[94:97]
	v_mfma_f32_16x16x32_bf16 v[90:93], v[244:247], v[180:183], v[90:93]
	v_mfma_f32_16x16x32_bf16 v[78:81], v[224:227], v[188:191], v[78:81]
	v_mfma_f32_16x16x32_bf16 v[74:77], v[244:247], v[188:191], v[74:77]
	v_mfma_f32_16x16x32_bf16 v[70:73], v[224:227], v[216:219], v[70:73]
	v_mfma_f32_16x16x32_bf16 v[66:69], v[244:247], v[216:219], v[66:69]
	s_setprio 0
	s_mov_b32 m0, s51
	v_lshl_add_u64 v[248:249], v[192:193], 0, s[26:27]
	s_barrier
	ds_read_b128 v[168:171], v145 offset:49152
	ds_read_b128 v[172:175], v145 offset:50176
	ds_read_b128 v[176:179], v145 offset:51200
	ds_read_b128 v[180:183], v145 offset:52224
	ds_read_b128 v[184:187], v145 offset:53248
	ds_read_b128 v[188:191], v145 offset:54272
	ds_read_b128 v[212:215], v145 offset:55296
	ds_read_b128 v[216:219], v145 offset:56320
	global_load_lds_dwordx4 v[248:249], off
	v_lshl_add_u64 v[192:193], v[192:193], 0, s[36:37]
	s_mov_b32 m0, s52
	s_nop 0
	global_load_lds_dwordx4 v[192:193], off
	s_barrier
; #define PG8_STAGE(bufoff, gbase, voff) do { _Pragma("unroll") for (int _i = 0; _i < 2; ++_i) \
;         __builtin_amdgcn_global_load_lds((const unsigned*)((const char*)(gbase) + (size_t)_i * p64##voff + (v##voff##_)), (LAS unsigned*)(lds + (bufoff) + ldsw + _i * 8192), 16, 0, 0); } while (0)
; #define PG8_MMA(ai, bj, At, Bt) do { __builtin_amdgcn_s_setprio(1); _Pragma("unroll") for (int m = 0; m < 4; ++m) _Pragma("unroll") for (int n = 0; n < 2; ++n) _Pragma("unroll") for (int k = 0; k < 2; ++k) \
;         acc[ai][bj][m][n] = __builtin_amdgcn_mfma_f32_16x16x32_bf16(Bt[n][k], At[m][k], acc[ai][bj][m][n], 0, 0, 0); __builtin_amdgcn_s_setprio(0); } while (0)
; #define PG8_WAIT_V(n) asm volatile("s_waitcnt vmcnt(" #n ")" ::: "memory")
; #define PG8_WAIT_L(n) asm volatile("s_waitcnt lgkmcnt(" #n ")" ::: "memory")
; #define PG8_BAR __builtin_amdgcn_s_barrier()
; #define PG8_SCHED __builtin_amdgcn_sched_barrier(0)
; template <class Epi, class Sched>
; DI void gemm_phase(LAS unsigned char* lds, const Gemm g, const Sched& S, const Epi& E, const int tid) {
;     ...
;         for (int t = 0; t < nt; t += 2) {
;             const bool last = (t == nt - 2);
;             const char* a1 = cA + (size_t)(t + 1) * kstep;
;             const char* a2 = last ? nA : cA + (size_t)(t + 2) * kstep; const char* b2 = last ? nB : cB + (size_t)(t + 2) * kstep;
;     ...
;             PG8_BAR; PG8_WAIT_L(0); PG8_MMA(1, 0, At, B0); PG8_BAR; PG8_SCHED;
;             PG8_STAGE(PG8_SB(1, 1), b3 + hstepB, offB);
;             PG8_WAIT_V(6); PG8_BAR; PG8_MMA(1, 1, At, B1); PG8_BAR;
	s_waitcnt lgkmcnt(0)
	s_setprio 1
	s_waitcnt lgkmcnt(0)
	v_mfma_f32_16x16x32_bf16 v[62:65], v[152:155], v[168:171], v[62:65]
	v_mfma_f32_16x16x32_bf16 v[58:61], v[160:163], v[168:171], v[58:61]
	v_mfma_f32_16x16x32_bf16 v[54:57], v[152:155], v[176:179], v[54:57]
	v_mfma_f32_16x16x32_bf16 v[50:53], v[160:163], v[176:179], v[50:53]
	v_mfma_f32_16x16x32_bf16 v[38:41], v[152:155], v[184:187], v[38:41]
	v_mfma_f32_16x16x32_bf16 v[34:37], v[160:163], v[184:187], v[34:37]
	v_mfma_f32_16x16x32_bf16 v[22:25], v[152:155], v[212:215], v[22:25]
	v_mfma_f32_16x16x32_bf16 v[18:21], v[160:163], v[212:215], v[18:21]
	v_mfma_f32_16x16x32_bf16 v[62:65], v[156:159], v[172:175], v[62:65]
	v_mfma_f32_16x16x32_bf16 v[58:61], v[164:167], v[172:175], v[58:61]
	v_mfma_f32_16x16x32_bf16 v[54:57], v[156:159], v[180:183], v[54:57]
	v_mfma_f32_16x16x32_bf16 v[50:53], v[164:167], v[180:183], v[50:53]
	v_mfma_f32_16x16x32_bf16 v[38:41], v[156:159], v[188:191], v[38:41]
	v_mfma_f32_16x16x32_bf16 v[34:37], v[164:167], v[188:191], v[34:37]
	v_mfma_f32_16x16x32_bf16 v[22:25], v[156:159], v[216:219], v[22:25]
	v_mfma_f32_16x16x32_bf16 v[18:21], v[164:167], v[216:219], v[18:21]
	s_setprio 0
	s_barrier
	s_add_i32 s59, s60, s46
	v_lshl_add_u64 v[152:153], v[146:147], 0, s[34:35]
	s_mov_b32 m0, s59
	v_lshl_add_u64 v[146:147], v[146:147], 0, s[18:19]
	global_load_lds_dwordx4 v[152:153], off
	s_add_i32 m0, s59, 0x2000
	s_nop 0
	global_load_lds_dwordx4 v[146:147], off
	s_waitcnt vmcnt(6)
	s_barrier
	s_setprio 1
	v_mfma_f32_16x16x32_bf16 v[46:49], v[220:223], v[168:171], v[46:49]
	v_mfma_f32_16x16x32_bf16 v[42:45], v[228:231], v[168:171], v[42:45]
	v_mfma_f32_16x16x32_bf16 v[30:33], v[220:223], v[176:179], v[30:33]
	v_mfma_f32_16x16x32_bf16 v[26:29], v[228:231], v[176:179], v[26:29]
	v_mfma_f32_16x16x32_bf16 v[14:17], v[220:223], v[184:187], v[14:17]
	v_mfma_f32_16x16x32_bf16 v[10:13], v[228:231], v[184:187], v[10:13]
	v_mfma_f32_16x16x32_bf16 v[6:9], v[220:223], v[212:215], v[6:9]
	v_mfma_f32_16x16x32_bf16 v[2:5], v[228:231], v[212:215], v[2:5]
	v_mfma_f32_16x16x32_bf16 v[46:49], v[224:227], v[172:175], v[46:49]
	v_mfma_f32_16x16x32_bf16 v[42:45], v[244:247], v[172:175], v[42:45]
	v_mfma_f32_16x16x32_bf16 v[30:33], v[224:227], v[180:183], v[30:33]
	v_mfma_f32_16x16x32_bf16 v[26:29], v[244:247], v[180:183], v[26:29]
	v_mfma_f32_16x16x32_bf16 v[14:17], v[224:227], v[188:191], v[14:17]
	v_mfma_f32_16x16x32_bf16 v[10:13], v[244:247], v[188:191], v[10:13]
	v_mfma_f32_16x16x32_bf16 v[6:9], v[224:227], v[216:219], v[6:9]
	v_mfma_f32_16x16x32_bf16 v[2:5], v[244:247], v[216:219], v[2:5]
	s_setprio 0
	s_add_i32 s58, s58, 2
	s_add_u32 s40, s40, 0x100
	s_addc_u32 s41, s41, 0
	s_add_u32 s42, s42, 0x100
	s_addc_u32 s43, s43, 0
	s_cmp_gt_u32 s58, 13
	s_barrier
	s_cbranch_scc0 .LBB0_568
; DI unsigned pk2(float lo, float hi) { f32x2 v = {lo, hi}; bf2_t b = __builtin_convertvector(v, bf2_t); return __builtin_bit_cast(unsigned, b); }
; #define PG8_WAIT_V(n) asm volatile("s_waitcnt vmcnt(" #n ")" ::: "memory")
; #define PG8_BAR __builtin_amdgcn_s_barrier()
;     DI void operator()(const f32x4 (&acc)[2][2][4][2], const Unit& u, int wr, int wc, int fr, int fq) const {
;         const int row0 = u.pm * BM + wr * 64 + fr, col0 = u.pn * BM + wc * 32 + 8 * fq;
; #pragma unroll
;         for (int ai = 0; ai < 2; ++ai)
; #pragma unroll
;             for (int m = 0; m < 4; ++m) { bf16_t* rowp = O + (size_t)(row0 + ai * HALF + m * 16) * ldc + col0;
; #pragma unroll
;                 for (int bj = 0; bj < 2; ++bj) { f32x4 v0 = acc[ai][bj][m][0], v1 = acc[ai][bj][m][1];
;                     if (ACT == 1) {
; #pragma unroll
;                         for (int j = 0; j < 4; ++j) { float a = fmaxf(v0[j], 0.f), b = fmaxf(v1[j], 0.f); v0[j] = a * a; v1[j] = b * b; } }
;                     u32x4 w; w.x = pk2(v0[0], v0[1]); w.y = pk2(v0[2], v0[3]); w.z = pk2(v1[0], v1[1]); w.w = pk2(v1[2], v1[3]);
;                     *(u32x4*)(rowp + bj * HALF) = w; } }
; template <class Epi, class Sched>
; DI void gemm_phase(LAS unsigned char* lds, const Gemm g, const Sched& S, const Epi& E, const int tid) {
;     ...
;         cur = nxt; cA = nA; cB = nB; ++ui;
;     }
;     PG8_WAIT_V(0);
;     if (wr == 0) PG8_BAR;
	v_lshl_add_u32 v146, s55, 8, v142
	v_lshl_or_b32 v152, s54, 8, v144
	v_ashrrev_i32_e32 v147, 31, v146
	v_readlane_b32 s40, v251, 21
	v_ashrrev_i32_e32 v153, 31, v152
	v_lshlrev_b64 v[154:155], 17, v[146:147]
	v_readlane_b32 s41, v251, 22
	v_lshlrev_b64 v[152:153], 1, v[152:153]
	s_mov_b32 s1, 0x1000000
	v_lshl_add_u64 v[154:155], s[40:41], 0, v[154:155]
	v_lshl_add_u64 v[154:155], v[154:155], 0, v[152:153]
	v_cvt_pk_bf16_f32 v62, v62, v63
	v_cvt_pk_bf16_f32 v63, v64, v65
	v_cvt_pk_bf16_f32 v64, v58, v59
	v_add_co_u32_e32 v58, vcc, s1, v154
	v_cvt_pk_bf16_f32 v70, v70, v71
	v_cvt_pk_bf16_f32 v71, v72, v73
	v_cvt_pk_bf16_f32 v72, v66, v67
	v_lshl_add_u64 v[66:67], v[154:155], 0, s[66:67]
	v_addc_co_u32_e32 v59, vcc, 0, v155, vcc
	v_cvt_pk_bf16_f32 v46, v46, v47
	v_cvt_pk_bf16_f32 v47, v48, v49
	v_cvt_pk_bf16_f32 v48, v42, v43
	v_cvt_pk_bf16_f32 v49, v44, v45
	s_mov_b32 s1, 0x1200000
	v_cvt_pk_bf16_f32 v110, v110, v111
	v_cvt_pk_bf16_f32 v111, v112, v113
	v_cvt_pk_bf16_f32 v112, v106, v107
	v_or_b32_e32 v106, 16, v146
	global_store_dwordx4 v[66:67], v[46:49], off offset:256 nt
	v_ashrrev_i32_e32 v107, 31, v106
	v_cvt_pk_bf16_f32 v94, v94, v95
	v_add_co_u32_e32 v48, vcc, s1, v154
	v_cvt_pk_bf16_f32 v95, v96, v97
	v_cvt_pk_bf16_f32 v96, v90, v91
	v_or_b32_e32 v90, 32, v146
	v_lshl_add_u64 v[46:47], v[154:155], 0, s[68:69]
	v_addc_co_u32_e32 v49, vcc, 0, v155, vcc
	v_cvt_pk_bf16_f32 v30, v30, v31
	v_cvt_pk_bf16_f32 v31, v32, v33
	v_cvt_pk_bf16_f32 v32, v26, v27
	v_cvt_pk_bf16_f32 v33, v28, v29
	s_mov_b32 s1, 0x1400000
	v_lshlrev_b64 v[106:107], 17, v[106:107]
	v_ashrrev_i32_e32 v91, 31, v90
	v_cvt_pk_bf16_f32 v78, v78, v79
	v_cvt_pk_bf16_f32 v79, v80, v81
	v_cvt_pk_bf16_f32 v80, v74, v75
	v_or_b32_e32 v74, 48, v146
	global_store_dwordx4 v[46:47], v[30:33], off offset:256 nt
	v_cvt_pk_bf16_f32 v113, v108, v109
	v_lshl_add_u64 v[106:107], s[40:41], 0, v[106:107]
	v_add_co_u32_e32 v32, vcc, s1, v154
	v_lshlrev_b64 v[90:91], 17, v[90:91]
	v_ashrrev_i32_e32 v75, 31, v74
	v_lshl_add_u64 v[30:31], v[154:155], 0, s[70:71]
	v_addc_co_u32_e32 v33, vcc, 0, v155, vcc
	v_cvt_pk_bf16_f32 v14, v14, v15
	v_cvt_pk_bf16_f32 v15, v16, v17
	v_cvt_pk_bf16_f32 v16, v10, v11
	v_cvt_pk_bf16_f32 v17, v12, v13
	s_mov_b32 s1, 0x1600000
	global_store_dwordx4 v[154:155], v[110:113], off offset:256 nt
	v_cvt_pk_bf16_f32 v97, v92, v93
	v_lshl_add_u64 v[90:91], s[40:41], 0, v[90:91]
	v_lshl_add_u64 v[110:111], v[106:107], 0, v[152:153]
	v_lshlrev_b64 v[74:75], 17, v[74:75]
	global_store_dwordx4 v[30:31], v[14:17], off offset:256 nt
	global_store_dwordx4 v[110:111], v[94:97], off offset:256 nt
	v_cvt_pk_bf16_f32 v81, v76, v77
	v_add_co_u32_e32 v16, vcc, s1, v154
	v_lshl_add_u64 v[94:95], v[90:91], 0, v[152:153]
	v_lshl_add_u64 v[74:75], s[40:41], 0, v[74:75]
	v_addc_co_u32_e32 v17, vcc, 0, v155, vcc
	v_cvt_pk_bf16_f32 v126, v126, v127
	v_cvt_pk_bf16_f32 v127, v128, v129
	v_cvt_pk_bf16_f32 v128, v122, v123
	v_cvt_pk_bf16_f32 v129, v124, v125
	v_cvt_pk_bf16_f32 v106, v118, v119
	v_cvt_pk_bf16_f32 v107, v120, v121
	v_cvt_pk_bf16_f32 v108, v114, v115
	v_cvt_pk_bf16_f32 v109, v116, v117
	v_cvt_pk_bf16_f32 v90, v102, v103
	v_cvt_pk_bf16_f32 v91, v104, v105
	v_cvt_pk_bf16_f32 v92, v98, v99
	v_cvt_pk_bf16_f32 v93, v100, v101
	global_store_dwordx4 v[94:95], v[78:81], off offset:256 nt
	v_cvt_pk_bf16_f32 v76, v82, v83
	v_cvt_pk_bf16_f32 v77, v84, v85
	v_lshl_add_u64 v[78:79], v[74:75], 0, v[152:153]
	v_cvt_pk_bf16_f32 v74, v86, v87
	v_cvt_pk_bf16_f32 v75, v88, v89
	v_cvt_pk_bf16_f32 v73, v68, v69
	v_cvt_pk_bf16_f32 v65, v60, v61
	v_cvt_pk_bf16_f32 v42, v54, v55
	v_cvt_pk_bf16_f32 v43, v56, v57
	v_cvt_pk_bf16_f32 v44, v50, v51
	v_cvt_pk_bf16_f32 v45, v52, v53
	v_cvt_pk_bf16_f32 v26, v38, v39
	v_cvt_pk_bf16_f32 v27, v40, v41
	v_cvt_pk_bf16_f32 v28, v34, v35
	v_cvt_pk_bf16_f32 v29, v36, v37
	v_lshl_add_u64 v[14:15], v[154:155], 0, s[72:73]
	v_cvt_pk_bf16_f32 v10, v22, v23
	v_cvt_pk_bf16_f32 v11, v24, v25
	v_cvt_pk_bf16_f32 v12, v18, v19
	v_cvt_pk_bf16_f32 v13, v20, v21
	v_cvt_pk_bf16_f32 v6, v6, v7
	v_cvt_pk_bf16_f32 v7, v8, v9
	v_cvt_pk_bf16_f32 v8, v2, v3
	v_cvt_pk_bf16_f32 v9, v4, v5
	s_and_b64 vcc, exec, s[38:39]
	s_mov_b32 s54, s0
	s_mov_b32 s55, s4
	s_mov_b64 s[42:43], s[8:9]
	s_mov_b64 s[40:41], s[6:7]
	global_store_dwordx4 v[154:155], v[126:129], off nt
	global_store_dwordx4 v[110:111], v[106:109], off nt
	global_store_dwordx4 v[94:95], v[90:93], off nt
	global_store_dwordx4 v[78:79], v[74:77], off nt
	global_store_dwordx4 v[78:79], v[70:73], off offset:256 nt
	global_store_dwordx4 v[58:59], v[62:65], off nt
	global_store_dwordx4 v[48:49], v[42:45], off nt
	global_store_dwordx4 v[32:33], v[26:29], off nt
	global_store_dwordx4 v[16:17], v[10:13], off nt
	global_store_dwordx4 v[14:15], v[6:9], off offset:256 nt
	s_cbranch_vccz .LBB0_565
	s_waitcnt vmcnt(0)
	s_cmpk_gt_u32 s2, 0xff
	s_cbranch_scc1 .LBB0_572
	s_barrier

;     DI bool next(int i, Unit& u) const { const int L = i * G + c; if (L >= 256) return false; u.pm = 0; u.pn = L; u.bofs = ((long)((L >> 3) * 2048 + 2 * (L & 7)) * 1024) * 2; return true; }
;     DI bool next(int i, Unit& u) const { Unit v; if (!base.next(i / 3, v)) return false; u.pm = v.pm; u.pn = (i % 3) * 4 + v.pn; u.bofs = -1; return true; }
; #define PG8_STAGE(bufoff, gbase, voff) do { _Pragma("unroll") for (int _i = 0; _i < 2; ++_i) \
;         __builtin_amdgcn_global_load_lds((const unsigned*)((const char*)(gbase) + (size_t)_i * p64##voff + (v##voff##_)), (LAS unsigned*)(lds + (bufoff) + ldsw + _i * 8192), 16, 0, 0); } while (0)
; #define PG8_LDA(dst, b, h) do { _Pragma("unroll") for (int m = 0; m < 4; ++m) _Pragma("unroll") for (int k = 0; k < 2; ++k) dst[m][k] = *(const LAS bf16x8*)(lds + PG8_SA(b, h) + aoff + m * 2048 + k * 1024); } while (0)
; #define PG8_LDB(dst, b, h) do { _Pragma("unroll") for (int n = 0; n < 2; ++n) _Pragma("unroll") for (int k = 0; k < 2; ++k) dst[n][k] = *(const LAS bf16x8*)(lds + PG8_SB(b, h) + boff + n * 2048 + k * 1024); } while (0)
; #define PG8_BAR __builtin_amdgcn_s_barrier()
; template <class Epi, class Sched>
; DI void gemm_phase(LAS unsigned char* lds, const Gemm g, const Sched& S, const Epi& E, const int tid) {
;     ...
;         const bool has_next = S.next(ui + 1, nxt);
;         const char* nA = has_next ? (const char*)g.A + (size_t)nxt.pm * tstepA : cA; const char* nB = has_next ? (const char*)g.Bt + (nxt.bofs >= 0 ? (size_t)nxt.bofs : (size_t)nxt.pn * tstepB) : cB;
;         for (int t = 0; t < nt; t += 2) {
;             const bool last = (t == nt - 2);
;             const char* a1 = cA + (size_t)(t + 1) * kstep;
;             const char* a2 = last ? nA : cA + (size_t)(t + 2) * kstep; const char* b2 = last ? nB : cB + (size_t)(t + 2) * kstep;
;             const char* a3 = a2 + kstep; const char* b3 = b2 + kstep;
;             PG8_LDB(B0, 0, 0); PG8_SCHED; PG8_LDA(At, 0, 0); PG8_STAGE(PG8_SA(1, 1), a1 + hstepA, offA);
;             PG8_WAIT_L(8); PG8_BAR; PG8_WAIT_L(0); PG8_MMA(0, 0, At, B0); PG8_BAR; PG8_SCHED;
;             PG8_LDB(B1, 0, 1); PG8_STAGE(PG8_SB(0, 0), b2, offB);
;             PG8_BAR; PG8_WAIT_L(0); PG8_MMA(0, 1, At, B1); PG8_BAR;
;             PG8_LDA(At, 0, 1); PG8_STAGE(PG8_SA(0, 0), a2, offA);
;             PG8_BAR; PG8_WAIT_L(0); PG8_MMA(1, 0, At, B0); PG8_BAR; PG8_SCHED;
.LBB0_578:
	s_add_u32 s55, s22, s38
	s_addc_u32 s56, s23, s39
	s_add_u32 s55, s55, 0x5a0100
	s_addc_u32 s56, s56, 0
	s_add_u32 s58, s52, s38
	s_addc_u32 s59, s53, s39
	s_add_i32 s62, 0, 0x10000
	v_add_u32_e32 v153, s62, v152
	ds_read_b128 v[154:157], v153
	ds_read_b128 v[158:161], v153 offset:1024
	ds_read_b128 v[162:165], v153 offset:2048
	ds_read_b128 v[166:169], v153 offset:3072
	s_cmpk_eq_i32 s38, 0x700
	s_cselect_b32 s57, s1, s56
	s_cselect_b32 s56, s0, s55
	s_cselect_b32 s59, s50, s59
	s_cselect_b32 s58, s51, s58
	v_lshl_add_u64 v[220:221], v[148:149], 0, s[38:39]
	s_mov_b64 s[60:61], 0x5e0080
	v_lshl_add_u64 v[222:223], v[220:221], 0, s[60:61]
	s_add_i32 m0, s41, 0xc000
	s_mov_b64 s[60:61], 0x600080
	ds_read_b128 v[170:173], v150
	ds_read_b128 v[174:177], v150 offset:1024
	ds_read_b128 v[178:181], v150 offset:2048
	ds_read_b128 v[182:185], v150 offset:3072
	ds_read_b128 v[186:189], v150 offset:4096
	ds_read_b128 v[190:193], v150 offset:5120
	ds_read_b128 v[212:215], v150 offset:6144
	ds_read_b128 v[216:219], v150 offset:7168
	global_load_lds_dwordx4 v[222:223], off
	v_lshl_add_u64 v[220:221], v[220:221], 0, s[60:61]
	s_add_i32 m0, s41, 0xe000
	s_nop 0
	global_load_lds_dwordx4 v[220:221], off
	s_waitcnt lgkmcnt(8)
	s_barrier
	s_waitcnt lgkmcnt(0)
	s_setprio 1
	s_waitcnt lgkmcnt(0)
	v_mfma_f32_16x16x32_bf16 v[126:129], v[154:157], v[170:173], v[126:129]
	v_mfma_f32_16x16x32_bf16 v[122:125], v[162:165], v[170:173], v[122:125]
	v_mfma_f32_16x16x32_bf16 v[118:121], v[154:157], v[178:181], v[118:121]
	v_mfma_f32_16x16x32_bf16 v[114:117], v[162:165], v[178:181], v[114:117]
	v_mfma_f32_16x16x32_bf16 v[102:105], v[154:157], v[186:189], v[102:105]
	v_mfma_f32_16x16x32_bf16 v[98:101], v[162:165], v[186:189], v[98:101]
	v_mfma_f32_16x16x32_bf16 v[86:89], v[154:157], v[212:215], v[86:89]
	v_mfma_f32_16x16x32_bf16 v[82:85], v[162:165], v[212:215], v[82:85]
	v_mfma_f32_16x16x32_bf16 v[126:129], v[158:161], v[174:177], v[126:129]
	v_mfma_f32_16x16x32_bf16 v[122:125], v[166:169], v[174:177], v[122:125]
	v_mfma_f32_16x16x32_bf16 v[118:121], v[158:161], v[182:185], v[118:121]
	v_mfma_f32_16x16x32_bf16 v[114:117], v[166:169], v[182:185], v[114:117]
	v_mfma_f32_16x16x32_bf16 v[102:105], v[158:161], v[190:193], v[102:105]
	v_mfma_f32_16x16x32_bf16 v[98:101], v[166:169], v[190:193], v[98:101]
	v_mfma_f32_16x16x32_bf16 v[86:89], v[158:161], v[216:219], v[86:89]
	v_mfma_f32_16x16x32_bf16 v[82:85], v[166:169], v[216:219], v[82:85]
	s_setprio 0
	s_barrier
	s_add_i32 s55, 0, 0x14000
	v_lshl_add_u64 v[248:249], s[58:59], 0, v[0:1]
	s_add_i32 s58, s62, s40
	v_add_u32_e32 v153, s55, v152
	s_mov_b32 m0, s58
	ds_read_b128 v[220:223], v153
	ds_read_b128 v[224:227], v153 offset:1024
	ds_read_b128 v[228:231], v153 offset:2048
	ds_read_b128 v[244:247], v153 offset:3072
	global_load_lds_dwordx4 v[248:249], off
	v_lshl_add_u64 v[198:199], v[248:249], 0, s[64:65]
	s_add_i32 m0, s58, 0x2000
	s_nop 0
	global_load_lds_dwordx4 v[198:199], off
	s_barrier
	s_waitcnt lgkmcnt(0)
	s_setprio 1
	s_waitcnt lgkmcnt(0)
	v_mfma_f32_16x16x32_bf16 v[110:113], v[220:223], v[170:173], v[110:113]
	v_mfma_f32_16x16x32_bf16 v[106:109], v[228:231], v[170:173], v[106:109]
	v_mfma_f32_16x16x32_bf16 v[94:97], v[220:223], v[178:181], v[94:97]
	v_mfma_f32_16x16x32_bf16 v[90:93], v[228:231], v[178:181], v[90:93]
	v_mfma_f32_16x16x32_bf16 v[78:81], v[220:223], v[186:189], v[78:81]
	v_mfma_f32_16x16x32_bf16 v[74:77], v[228:231], v[186:189], v[74:77]
	v_mfma_f32_16x16x32_bf16 v[70:73], v[220:223], v[212:215], v[70:73]
	v_mfma_f32_16x16x32_bf16 v[66:69], v[228:231], v[212:215], v[66:69]
	v_mfma_f32_16x16x32_bf16 v[110:113], v[224:227], v[174:177], v[110:113]
	v_mfma_f32_16x16x32_bf16 v[106:109], v[244:247], v[174:177], v[106:109]
	v_mfma_f32_16x16x32_bf16 v[94:97], v[224:227], v[182:185], v[94:97]
	v_mfma_f32_16x16x32_bf16 v[90:93], v[244:247], v[182:185], v[90:93]
	v_mfma_f32_16x16x32_bf16 v[78:81], v[224:227], v[190:193], v[78:81]
	v_mfma_f32_16x16x32_bf16 v[74:77], v[244:247], v[190:193], v[74:77]
	v_mfma_f32_16x16x32_bf16 v[70:73], v[224:227], v[216:219], v[70:73]
	v_mfma_f32_16x16x32_bf16 v[66:69], v[244:247], v[216:219], v[66:69]
	s_setprio 0
	s_mov_b32 m0, s41
	v_lshl_add_u64 v[198:199], s[56:57], 0, v[130:131]
	s_barrier
	ds_read_b128 v[170:173], v150 offset:16384
	ds_read_b128 v[174:177], v150 offset:17408
	ds_read_b128 v[178:181], v150 offset:18432
	ds_read_b128 v[182:185], v150 offset:19456
	ds_read_b128 v[186:189], v150 offset:20480
	ds_read_b128 v[190:193], v150 offset:21504
	ds_read_b128 v[212:215], v150 offset:22528
	ds_read_b128 v[216:219], v150 offset:23552
	global_load_lds_dwordx4 v[198:199], off
	v_lshl_add_u64 v[200:201], v[198:199], 0, s[10:11]
	s_mov_b32 m0, s42
	s_nop 0
	global_load_lds_dwordx4 v[200:201], off
	s_barrier
	s_waitcnt lgkmcnt(0)
	s_setprio 1
	s_waitcnt lgkmcnt(0)
	v_mfma_f32_16x16x32_bf16 v[62:65], v[154:157], v[170:173], v[62:65]
	v_mfma_f32_16x16x32_bf16 v[58:61], v[162:165], v[170:173], v[58:61]
	v_mfma_f32_16x16x32_bf16 v[54:57], v[154:157], v[178:181], v[54:57]
	v_mfma_f32_16x16x32_bf16 v[50:53], v[162:165], v[178:181], v[50:53]
	v_mfma_f32_16x16x32_bf16 v[38:41], v[154:157], v[186:189], v[38:41]
	v_mfma_f32_16x16x32_bf16 v[34:37], v[162:165], v[186:189], v[34:37]
	v_mfma_f32_16x16x32_bf16 v[22:25], v[154:157], v[212:215], v[22:25]
	v_mfma_f32_16x16x32_bf16 v[18:21], v[162:165], v[212:215], v[18:21]
	v_mfma_f32_16x16x32_bf16 v[62:65], v[158:161], v[174:177], v[62:65]
	v_mfma_f32_16x16x32_bf16 v[58:61], v[166:169], v[174:177], v[58:61]
	v_mfma_f32_16x16x32_bf16 v[54:57], v[158:161], v[182:185], v[54:57]
	v_mfma_f32_16x16x32_bf16 v[50:53], v[166:169], v[182:185], v[50:53]
	v_mfma_f32_16x16x32_bf16 v[38:41], v[158:161], v[190:193], v[38:41]
	v_mfma_f32_16x16x32_bf16 v[34:37], v[166:169], v[190:193], v[34:37]
	v_mfma_f32_16x16x32_bf16 v[22:25], v[158:161], v[216:219], v[22:25]
	v_mfma_f32_16x16x32_bf16 v[18:21], v[166:169], v[216:219], v[18:21]
	s_setprio 0
	s_barrier
; #define PG8_STAGE(bufoff, gbase, voff) do { _Pragma("unroll") for (int _i = 0; _i < 2; ++_i) \
;         __builtin_amdgcn_global_load_lds((const unsigned*)((const char*)(gbase) + (size_t)_i * p64##voff + (v##voff##_)), (LAS unsigned*)(lds + (bufoff) + ldsw + _i * 8192), 16, 0, 0); } while (0)
; #define PG8_LDA(dst, b, h) do { _Pragma("unroll") for (int m = 0; m < 4; ++m) _Pragma("unroll") for (int k = 0; k < 2; ++k) dst[m][k] = *(const LAS bf16x8*)(lds + PG8_SA(b, h) + aoff + m * 2048 + k * 1024); } while (0)
; #define PG8_LDB(dst, b, h) do { _Pragma("unroll") for (int n = 0; n < 2; ++n) _Pragma("unroll") for (int k = 0; k < 2; ++k) dst[n][k] = *(const LAS bf16x8*)(lds + PG8_SB(b, h) + boff + n * 2048 + k * 1024); } while (0)
; #define PG8_MMA(ai, bj, At, Bt) do { __builtin_amdgcn_s_setprio(1); _Pragma("unroll") for (int m = 0; m < 4; ++m) _Pragma("unroll") for (int n = 0; n < 2; ++n) _Pragma("unroll") for (int k = 0; k < 2; ++k) \
;         acc[ai][bj][m][n] = __builtin_amdgcn_mfma_f32_16x16x32_bf16(Bt[n][k], At[m][k], acc[ai][bj][m][n], 0, 0, 0); __builtin_amdgcn_s_setprio(0); } while (0)
; #define PG8_WAIT_V(n) asm volatile("s_waitcnt vmcnt(" #n ")" ::: "memory")
; #define PG8_WAIT_L(n) asm volatile("s_waitcnt lgkmcnt(" #n ")" ::: "memory")
; #define PG8_BAR __builtin_amdgcn_s_barrier()
; #define PG8_SCHED __builtin_amdgcn_sched_barrier(0)
; template <class Epi, class Sched>
; DI void gemm_phase(LAS unsigned char* lds, const Gemm g, const Sched& S, const Epi& E, const int tid) {
;     ...
;             PG8_STAGE(PG8_SB(0, 1), b2 + hstepB, offB);
;             PG8_WAIT_V(6); PG8_BAR; PG8_MMA(1, 1, At, B1); PG8_BAR;
;             PG8_LDB(B0, 1, 0); PG8_SCHED; PG8_LDA(At, 1, 0); PG8_STAGE(PG8_SA(0, 1), a2 + hstepA, offA);
;             PG8_WAIT_L(8); PG8_BAR; PG8_WAIT_L(0); PG8_MMA(0, 0, At, B0); PG8_BAR; PG8_SCHED;
;             PG8_LDB(B1, 1, 1); PG8_STAGE(PG8_SB(1, 0), b3, offB);
;             PG8_BAR; PG8_WAIT_L(0); PG8_MMA(0, 1, At, B1); PG8_BAR;
;             PG8_LDA(At, 1, 1); PG8_STAGE(PG8_SA(1, 0), a3, offA);
	s_add_i32 s55, s55, s40
	v_lshl_add_u64 v[154:155], v[248:249], 0, s[66:67]
	s_mov_b32 m0, s55
	s_nop 0
	global_load_lds_dwordx4 v[154:155], off
	v_lshl_add_u64 v[154:155], v[248:249], 0, s[68:69]
	s_add_i32 m0, s55, 0x2000
	s_nop 0
	global_load_lds_dwordx4 v[154:155], off
	s_waitcnt vmcnt(6)
	s_barrier
	s_setprio 1
	v_mfma_f32_16x16x32_bf16 v[46:49], v[220:223], v[170:173], v[46:49]
	v_mfma_f32_16x16x32_bf16 v[42:45], v[228:231], v[170:173], v[42:45]
	v_mfma_f32_16x16x32_bf16 v[30:33], v[220:223], v[178:181], v[30:33]
	v_mfma_f32_16x16x32_bf16 v[26:29], v[228:231], v[178:181], v[26:29]
	v_mfma_f32_16x16x32_bf16 v[14:17], v[220:223], v[186:189], v[14:17]
	v_mfma_f32_16x16x32_bf16 v[10:13], v[228:231], v[186:189], v[10:13]
	v_mfma_f32_16x16x32_bf16 v[6:9], v[220:223], v[212:215], v[6:9]
	v_mfma_f32_16x16x32_bf16 v[2:5], v[228:231], v[212:215], v[2:5]
	v_mfma_f32_16x16x32_bf16 v[46:49], v[224:227], v[174:177], v[46:49]
	v_mfma_f32_16x16x32_bf16 v[42:45], v[244:247], v[174:177], v[42:45]
	v_mfma_f32_16x16x32_bf16 v[30:33], v[224:227], v[182:185], v[30:33]
	v_mfma_f32_16x16x32_bf16 v[26:29], v[244:247], v[182:185], v[26:29]
	v_mfma_f32_16x16x32_bf16 v[14:17], v[224:227], v[190:193], v[14:17]
	v_mfma_f32_16x16x32_bf16 v[10:13], v[244:247], v[190:193], v[10:13]
	v_mfma_f32_16x16x32_bf16 v[6:9], v[224:227], v[216:219], v[6:9]
	v_mfma_f32_16x16x32_bf16 v[2:5], v[244:247], v[216:219], v[2:5]
	s_setprio 0
	s_add_i32 s55, 0, 0x18000
	v_add_u32_e32 v153, s55, v152
	s_barrier
	ds_read_b128 v[154:157], v153
	ds_read_b128 v[158:161], v153 offset:1024
	ds_read_b128 v[162:165], v153 offset:2048
	ds_read_b128 v[166:169], v153 offset:3072
	s_mov_b32 m0, s43
	v_lshl_add_u64 v[200:201], v[198:199], 0, s[24:25]
	ds_read_b128 v[170:173], v150 offset:32768
	ds_read_b128 v[174:177], v150 offset:33792
	ds_read_b128 v[178:181], v150 offset:34816
	ds_read_b128 v[182:185], v150 offset:35840
	ds_read_b128 v[186:189], v150 offset:36864
	ds_read_b128 v[190:193], v150 offset:37888
	ds_read_b128 v[212:215], v150 offset:38912
	ds_read_b128 v[216:219], v150 offset:39936
	global_load_lds_dwordx4 v[200:201], off
	v_lshl_add_u64 v[200:201], v[198:199], 0, s[28:29]
	s_mov_b32 m0, s44
	s_nop 0
	global_load_lds_dwordx4 v[200:201], off
	s_waitcnt lgkmcnt(8)
	s_barrier
	s_waitcnt lgkmcnt(0)
	s_setprio 1
	s_waitcnt lgkmcnt(0)
	v_mfma_f32_16x16x32_bf16 v[126:129], v[154:157], v[170:173], v[126:129]
	v_mfma_f32_16x16x32_bf16 v[122:125], v[162:165], v[170:173], v[122:125]
	v_mfma_f32_16x16x32_bf16 v[118:121], v[154:157], v[178:181], v[118:121]
	v_mfma_f32_16x16x32_bf16 v[114:117], v[162:165], v[178:181], v[114:117]
	v_mfma_f32_16x16x32_bf16 v[102:105], v[154:157], v[186:189], v[102:105]
	v_mfma_f32_16x16x32_bf16 v[98:101], v[162:165], v[186:189], v[98:101]
	v_mfma_f32_16x16x32_bf16 v[86:89], v[154:157], v[212:215], v[86:89]
	v_mfma_f32_16x16x32_bf16 v[82:85], v[162:165], v[212:215], v[82:85]
	v_mfma_f32_16x16x32_bf16 v[126:129], v[158:161], v[174:177], v[126:129]
	v_mfma_f32_16x16x32_bf16 v[122:125], v[166:169], v[174:177], v[122:125]
	v_mfma_f32_16x16x32_bf16 v[118:121], v[158:161], v[182:185], v[118:121]
	v_mfma_f32_16x16x32_bf16 v[114:117], v[166:169], v[182:185], v[114:117]
	v_mfma_f32_16x16x32_bf16 v[102:105], v[158:161], v[190:193], v[102:105]
	v_mfma_f32_16x16x32_bf16 v[98:101], v[166:169], v[190:193], v[98:101]
	v_mfma_f32_16x16x32_bf16 v[86:89], v[158:161], v[216:219], v[86:89]
	v_mfma_f32_16x16x32_bf16 v[82:85], v[166:169], v[216:219], v[82:85]
	s_setprio 0
	s_barrier
	s_add_i32 s56, 0, 0x1c000
	s_add_i32 s55, s55, s40
	v_add_u32_e32 v153, s56, v152
	v_lshl_add_u64 v[200:201], v[248:249], 0, s[26:27]
	s_mov_b32 m0, s55
	ds_read_b128 v[220:223], v153
	ds_read_b128 v[224:227], v153 offset:1024
	ds_read_b128 v[228:231], v153 offset:2048
	ds_read_b128 v[244:247], v153 offset:3072
	global_load_lds_dwordx4 v[200:201], off
	v_lshl_add_u64 v[200:201], v[248:249], 0, s[70:71]
	s_add_i32 m0, s55, 0x2000
	s_nop 0
	global_load_lds_dwordx4 v[200:201], off
	s_barrier
	s_waitcnt lgkmcnt(0)
	s_setprio 1
	s_waitcnt lgkmcnt(0)
	v_mfma_f32_16x16x32_bf16 v[110:113], v[220:223], v[170:173], v[110:113]
	v_mfma_f32_16x16x32_bf16 v[106:109], v[228:231], v[170:173], v[106:109]
	v_mfma_f32_16x16x32_bf16 v[94:97], v[220:223], v[178:181], v[94:97]
	v_mfma_f32_16x16x32_bf16 v[90:93], v[228:231], v[178:181], v[90:93]
	v_mfma_f32_16x16x32_bf16 v[78:81], v[220:223], v[186:189], v[78:81]
	v_mfma_f32_16x16x32_bf16 v[74:77], v[228:231], v[186:189], v[74:77]
	v_mfma_f32_16x16x32_bf16 v[70:73], v[220:223], v[212:215], v[70:73]
	v_mfma_f32_16x16x32_bf16 v[66:69], v[228:231], v[212:215], v[66:69]
	v_mfma_f32_16x16x32_bf16 v[110:113], v[224:227], v[174:177], v[110:113]
	v_mfma_f32_16x16x32_bf16 v[106:109], v[244:247], v[174:177], v[106:109]
	v_mfma_f32_16x16x32_bf16 v[94:97], v[224:227], v[182:185], v[94:97]
	v_mfma_f32_16x16x32_bf16 v[90:93], v[244:247], v[182:185], v[90:93]
	v_mfma_f32_16x16x32_bf16 v[78:81], v[224:227], v[190:193], v[78:81]
	v_mfma_f32_16x16x32_bf16 v[74:77], v[244:247], v[190:193], v[74:77]
	v_mfma_f32_16x16x32_bf16 v[70:73], v[224:227], v[216:219], v[70:73]
	v_mfma_f32_16x16x32_bf16 v[66:69], v[244:247], v[216:219], v[66:69]
	s_setprio 0
	s_mov_b32 m0, s45
	v_lshl_add_u64 v[200:201], v[198:199], 0, s[26:27]
	s_barrier
	ds_read_b128 v[170:173], v150 offset:49152
	ds_read_b128 v[174:177], v150 offset:50176
	ds_read_b128 v[178:181], v150 offset:51200
	ds_read_b128 v[182:185], v150 offset:52224
	ds_read_b128 v[186:189], v150 offset:53248
	ds_read_b128 v[190:193], v150 offset:54272
	ds_read_b128 v[212:215], v150 offset:55296
	ds_read_b128 v[216:219], v150 offset:56320
	global_load_lds_dwordx4 v[200:201], off
	v_lshl_add_u64 v[198:199], v[198:199], 0, s[36:37]
	s_mov_b32 m0, s46
	s_nop 0
	global_load_lds_dwordx4 v[198:199], off
	s_barrier
; DI unsigned pk2(float lo, float hi) { f32x2 v = {lo, hi}; bf2_t b = __builtin_convertvector(v, bf2_t); return __builtin_bit_cast(unsigned, b); }
; #define PG8_STAGE(bufoff, gbase, voff) do { _Pragma("unroll") for (int _i = 0; _i < 2; ++_i) \
;         __builtin_amdgcn_global_load_lds((const unsigned*)((const char*)(gbase) + (size_t)_i * p64##voff + (v##voff##_)), (LAS unsigned*)(lds + (bufoff) + ldsw + _i * 8192), 16, 0, 0); } while (0)
; #define PG8_MMA(ai, bj, At, Bt) do { __builtin_amdgcn_s_setprio(1); _Pragma("unroll") for (int m = 0; m < 4; ++m) _Pragma("unroll") for (int n = 0; n < 2; ++n) _Pragma("unroll") for (int k = 0; k < 2; ++k) \
;         acc[ai][bj][m][n] = __builtin_amdgcn_mfma_f32_16x16x32_bf16(Bt[n][k], At[m][k], acc[ai][bj][m][n], 0, 0, 0); __builtin_amdgcn_s_setprio(0); } while (0)
; #define PG8_WAIT_V(n) asm volatile("s_waitcnt vmcnt(" #n ")" ::: "memory")
; #define PG8_WAIT_L(n) asm volatile("s_waitcnt lgkmcnt(" #n ")" ::: "memory")
; #define PG8_BAR __builtin_amdgcn_s_barrier()
; #define PG8_SCHED __builtin_amdgcn_sched_barrier(0)
;     DI void operator()(const f32x4 (&acc)[2][2][4][2], const Unit& u, int wr, int wc, int fr, int fq) const {
;         const int row0 = u.pm * BM + wr * 64 + fr, col0 = u.pn * BM + wc * 32 + 8 * fq;
; #pragma unroll
;         for (int ai = 0; ai < 2; ++ai)
; #pragma unroll
;             for (int m = 0; m < 4; ++m) { bf16_t* rowp = O + (size_t)(row0 + ai * HALF + m * 16) * ldc + col0;
; #pragma unroll
;                 for (int bj = 0; bj < 2; ++bj) { f32x4 v0 = acc[ai][bj][m][0], v1 = acc[ai][bj][m][1];
;                     if (ACT == 1) {
; #pragma unroll
;                         for (int j = 0; j < 4; ++j) { float a = fmaxf(v0[j], 0.f), b = fmaxf(v1[j], 0.f); v0[j] = a * a; v1[j] = b * b; } }
;                     u32x4 w; w.x = pk2(v0[0], v0[1]); w.y = pk2(v0[2], v0[3]); w.z = pk2(v1[0], v1[1]); w.w = pk2(v1[2], v1[3]);
;                     *(u32x4*)(rowp + bj * HALF) = w; } }
; template <class Epi, class Sched>
; DI void gemm_phase(LAS unsigned char* lds, const Gemm g, const Sched& S, const Epi& E, const int tid) {
;     ...
;             PG8_BAR; PG8_WAIT_L(0); PG8_MMA(1, 0, At, B0); PG8_BAR; PG8_SCHED;
;             PG8_STAGE(PG8_SB(1, 1), b3 + hstepB, offB);
;             PG8_WAIT_V(6); PG8_BAR; PG8_MMA(1, 1, At, B1); PG8_BAR;
	s_waitcnt lgkmcnt(0)
	s_setprio 1
	s_waitcnt lgkmcnt(0)
	v_mfma_f32_16x16x32_bf16 v[62:65], v[154:157], v[170:173], v[62:65]
	v_mfma_f32_16x16x32_bf16 v[58:61], v[162:165], v[170:173], v[58:61]
	v_mfma_f32_16x16x32_bf16 v[54:57], v[154:157], v[178:181], v[54:57]
	v_mfma_f32_16x16x32_bf16 v[50:53], v[162:165], v[178:181], v[50:53]
	v_mfma_f32_16x16x32_bf16 v[38:41], v[154:157], v[186:189], v[38:41]
	v_mfma_f32_16x16x32_bf16 v[34:37], v[162:165], v[186:189], v[34:37]
	v_mfma_f32_16x16x32_bf16 v[22:25], v[154:157], v[212:215], v[22:25]
	v_mfma_f32_16x16x32_bf16 v[18:21], v[162:165], v[212:215], v[18:21]
	v_mfma_f32_16x16x32_bf16 v[62:65], v[158:161], v[174:177], v[62:65]
	v_mfma_f32_16x16x32_bf16 v[58:61], v[166:169], v[174:177], v[58:61]
	v_mfma_f32_16x16x32_bf16 v[54:57], v[158:161], v[182:185], v[54:57]
	v_mfma_f32_16x16x32_bf16 v[50:53], v[166:169], v[182:185], v[50:53]
	v_mfma_f32_16x16x32_bf16 v[38:41], v[158:161], v[190:193], v[38:41]
	v_mfma_f32_16x16x32_bf16 v[34:37], v[166:169], v[190:193], v[34:37]
	v_mfma_f32_16x16x32_bf16 v[22:25], v[158:161], v[216:219], v[22:25]
	v_mfma_f32_16x16x32_bf16 v[18:21], v[166:169], v[216:219], v[18:21]
	s_setprio 0
	s_barrier
	s_add_i32 s55, s56, s40
	v_lshl_add_u64 v[154:155], v[248:249], 0, s[72:73]
	s_mov_b32 m0, s55
	s_nop 0
	global_load_lds_dwordx4 v[154:155], off
	v_lshl_add_u64 v[154:155], v[248:249], 0, s[74:75]
	s_add_i32 m0, s55, 0x2000
	s_nop 0
	global_load_lds_dwordx4 v[154:155], off
	s_waitcnt vmcnt(6)
	s_barrier
	s_setprio 1
	v_mfma_f32_16x16x32_bf16 v[46:49], v[220:223], v[170:173], v[46:49]
	v_mfma_f32_16x16x32_bf16 v[42:45], v[228:231], v[170:173], v[42:45]
	v_mfma_f32_16x16x32_bf16 v[30:33], v[220:223], v[178:181], v[30:33]
	v_mfma_f32_16x16x32_bf16 v[26:29], v[228:231], v[178:181], v[26:29]
	v_mfma_f32_16x16x32_bf16 v[14:17], v[220:223], v[186:189], v[14:17]
	v_mfma_f32_16x16x32_bf16 v[10:13], v[228:231], v[186:189], v[10:13]
	v_mfma_f32_16x16x32_bf16 v[6:9], v[220:223], v[212:215], v[6:9]
	v_mfma_f32_16x16x32_bf16 v[2:5], v[228:231], v[212:215], v[2:5]
	v_mfma_f32_16x16x32_bf16 v[46:49], v[224:227], v[174:177], v[46:49]
	v_mfma_f32_16x16x32_bf16 v[42:45], v[244:247], v[174:177], v[42:45]
	v_mfma_f32_16x16x32_bf16 v[30:33], v[224:227], v[182:185], v[30:33]
	v_mfma_f32_16x16x32_bf16 v[26:29], v[244:247], v[182:185], v[26:29]
	v_mfma_f32_16x16x32_bf16 v[14:17], v[224:227], v[190:193], v[14:17]
	v_mfma_f32_16x16x32_bf16 v[10:13], v[244:247], v[190:193], v[10:13]
	v_mfma_f32_16x16x32_bf16 v[6:9], v[224:227], v[216:219], v[6:9]
	v_mfma_f32_16x16x32_bf16 v[2:5], v[244:247], v[216:219], v[2:5]
	s_setprio 0
	s_add_i32 s54, s54, 2
	s_add_u32 s38, s38, 0x100
	s_addc_u32 s39, s39, 0
	s_cmp_gt_u32 s54, 13
	s_barrier
	s_cbranch_scc0 .LBB0_578
	v_lshl_or_b32 v154, s49, 8, v151
	v_ashrrev_i32_e32 v155, 31, v154
	v_lshlrev_b64 v[154:155], 1, v[154:155]
	v_lshl_add_u64 v[156:157], v[132:133], 0, v[154:155]
	v_cvt_pk_bf16_f32 v110, v110, v111
	v_cvt_pk_bf16_f32 v111, v112, v113
	v_cvt_pk_bf16_f32 v112, v106, v107
	v_cvt_pk_bf16_f32 v113, v108, v109
	v_cvt_pk_bf16_f32 v70, v70, v71
	v_cvt_pk_bf16_f32 v71, v72, v73
	v_cvt_pk_bf16_f32 v72, v66, v67
	v_lshl_add_u64 v[66:67], v[140:141], 0, v[154:155]
	v_cvt_pk_bf16_f32 v46, v46, v47
	v_cvt_pk_bf16_f32 v47, v48, v49
	v_cvt_pk_bf16_f32 v48, v42, v43
	v_cvt_pk_bf16_f32 v49, v44, v45
	global_store_dwordx4 v[156:157], v[110:113], off offset:256 nt
	v_cvt_pk_bf16_f32 v94, v94, v95
	v_cvt_pk_bf16_f32 v95, v96, v97
	v_lshl_add_u64 v[110:111], v[134:135], 0, v[154:155]
	v_cvt_pk_bf16_f32 v96, v90, v91
	v_cvt_pk_bf16_f32 v97, v92, v93
	global_store_dwordx4 v[66:67], v[46:49], off offset:256 nt
	v_cvt_pk_bf16_f32 v30, v30, v31
	v_cvt_pk_bf16_f32 v31, v32, v33
	v_lshl_add_u64 v[46:47], v[142:143], 0, v[154:155]
	v_cvt_pk_bf16_f32 v32, v26, v27
	v_cvt_pk_bf16_f32 v33, v28, v29
	global_store_dwordx4 v[110:111], v[94:97], off offset:256 nt
	v_cvt_pk_bf16_f32 v78, v78, v79
	v_cvt_pk_bf16_f32 v79, v80, v81
	v_lshl_add_u64 v[94:95], v[136:137], 0, v[154:155]
	v_cvt_pk_bf16_f32 v80, v74, v75
	v_cvt_pk_bf16_f32 v81, v76, v77
	global_store_dwordx4 v[46:47], v[30:33], off offset:256 nt
	v_cvt_pk_bf16_f32 v14, v14, v15
	v_cvt_pk_bf16_f32 v15, v16, v17
	v_lshl_add_u64 v[30:31], v[144:145], 0, v[154:155]
	v_cvt_pk_bf16_f32 v16, v10, v11
	v_cvt_pk_bf16_f32 v17, v12, v13
	v_cvt_pk_bf16_f32 v126, v126, v127
	v_cvt_pk_bf16_f32 v127, v128, v129
	v_cvt_pk_bf16_f32 v128, v122, v123
	v_cvt_pk_bf16_f32 v129, v124, v125
	v_cvt_pk_bf16_f32 v106, v118, v119
	v_cvt_pk_bf16_f32 v107, v120, v121
	v_cvt_pk_bf16_f32 v108, v114, v115
	v_cvt_pk_bf16_f32 v109, v116, v117
	v_cvt_pk_bf16_f32 v90, v102, v103
	v_cvt_pk_bf16_f32 v91, v104, v105
	v_cvt_pk_bf16_f32 v92, v98, v99
	v_cvt_pk_bf16_f32 v93, v100, v101
	global_store_dwordx4 v[94:95], v[78:81], off offset:256 nt
	v_cvt_pk_bf16_f32 v74, v86, v87
	v_cvt_pk_bf16_f32 v75, v88, v89
	v_lshl_add_u64 v[78:79], v[138:139], 0, v[154:155]
	v_cvt_pk_bf16_f32 v76, v82, v83
	v_cvt_pk_bf16_f32 v77, v84, v85
	v_cvt_pk_bf16_f32 v73, v68, v69
	v_cvt_pk_bf16_f32 v62, v62, v63
	v_cvt_pk_bf16_f32 v63, v64, v65
	v_cvt_pk_bf16_f32 v64, v58, v59
	v_cvt_pk_bf16_f32 v65, v60, v61
	v_cvt_pk_bf16_f32 v42, v54, v55
	v_cvt_pk_bf16_f32 v43, v56, v57
	v_cvt_pk_bf16_f32 v44, v50, v51
	v_cvt_pk_bf16_f32 v45, v52, v53
	v_cvt_pk_bf16_f32 v26, v38, v39
	v_cvt_pk_bf16_f32 v27, v40, v41
	v_cvt_pk_bf16_f32 v28, v34, v35
	v_cvt_pk_bf16_f32 v29, v36, v37
	global_store_dwordx4 v[30:31], v[14:17], off offset:256 nt
	v_cvt_pk_bf16_f32 v10, v22, v23
	v_cvt_pk_bf16_f32 v11, v24, v25
	v_lshl_add_u64 v[14:15], v[146:147], 0, v[154:155]
	v_cvt_pk_bf16_f32 v12, v18, v19
	v_cvt_pk_bf16_f32 v13, v20, v21
	v_cvt_pk_bf16_f32 v6, v6, v7
	v_cvt_pk_bf16_f32 v7, v8, v9
	v_cvt_pk_bf16_f32 v8, v2, v3
	v_cvt_pk_bf16_f32 v9, v4, v5
	s_and_b64 vcc, exec, s[6:7]
	s_mov_b32 s49, s48
	global_store_dwordx4 v[156:157], v[126:129], off nt
	global_store_dwordx4 v[110:111], v[106:109], off nt
	global_store_dwordx4 v[94:95], v[90:93], off nt
	global_store_dwordx4 v[78:79], v[74:77], off nt
	global_store_dwordx4 v[78:79], v[70:73], off offset:256 nt
	global_store_dwordx4 v[66:67], v[62:65], off nt
	global_store_dwordx4 v[46:47], v[42:45], off nt
	global_store_dwordx4 v[30:31], v[26:29], off nt
	global_store_dwordx4 v[14:15], v[10:13], off nt
	global_store_dwordx4 v[14:15], v[6:9], off offset:256 nt
	s_cbranch_vccz .LBB0_577
	s_waitcnt vmcnt(0)
	s_cmpk_gt_u32 s2, 0xff
	s_cbranch_scc1 .LBB0_582
	s_barrier
